# adaLN partial-sum loop: 32 weight row loads in flight with LDS operands one step ahead
# speedup vs baseline: 1.0115x; 1.0039x over previous
; __device__ __forceinline__ void mod_item(const int tid, float* cs, const Params& p, int item) {
;     const int l = item / 96, rem = item % 96, s = rem / 12, cb = rem % 12, k0 = s * 256, col = cb * 512 + tid;
;     __syncthreads();
; #pragma unroll
;     for (int i = 0; i < 8; ++i) { const int idx = tid + 512 * i, r = idx & 15, k = idx >> 4;
;         const float x = (r < 8 ? p.in[2] + r * 2048 : p.in[3] + (r - 8) * 2048)[k0 + k]; cs[idx] = x / (1.f + expf(-x)); }
;     __syncthreads();
.LBB0_828:
	s_mul_hi_i32 s4, s20, 0x2aaaaaab
	s_lshr_b32 s5, s4, 31
	s_ashr_i32 s4, s4, 4
	s_add_i32 s14, s4, s5
	s_mul_i32 s4, s14, 0x60
	s_sub_i32 s4, s20, s4
	s_mul_i32 s5, s4, 43
	s_sext_i32_i16 s15, s5
	s_ashr_i32 s15, s15, 9
	s_bfe_u32 s5, s5, 0x1000f
	s_add_i32 s21, s15, s5
	s_sext_i32_i16 s15, s21
	s_lshl_b32 s5, s15, 8
	v_add_u32_e32 v4, s5, v39
	v_ashrrev_i32_e32 v5, 31, v4
	v_add_u32_e32 v6, s5, v41
	v_add_u32_e32 v8, s5, v42
	v_lshl_add_u64 v[4:5], v[4:5], 2, v[2:3]
	v_ashrrev_i32_e32 v7, 31, v6
	v_ashrrev_i32_e32 v9, 31, v8
	s_waitcnt lgkmcnt(0)
	s_barrier
	v_lshl_add_u64 v[6:7], v[6:7], 2, v[2:3]
	v_lshl_add_u64 v[8:9], v[8:9], 2, v[2:3]
	global_load_dword v5, v[4:5], off
	s_nop 0
	global_load_dword v16, v[6:7], off
	global_load_dword v17, v[8:9], off
	v_add_u32_e32 v6, s5, v43
	v_add_u32_e32 v8, s5, v44
	v_add_u32_e32 v10, s5, v45
	v_add_u32_e32 v12, s5, v46
	v_add_u32_e32 v14, s5, v47
	v_ashrrev_i32_e32 v7, 31, v6
	v_ashrrev_i32_e32 v9, 31, v8
	v_ashrrev_i32_e32 v11, 31, v10
	v_ashrrev_i32_e32 v13, 31, v12
	v_ashrrev_i32_e32 v15, 31, v14
	v_lshl_add_u64 v[6:7], v[6:7], 2, v[2:3]
	v_lshl_add_u64 v[8:9], v[8:9], 2, v[2:3]
	v_lshl_add_u64 v[10:11], v[10:11], 2, v[2:3]
	v_lshl_add_u64 v[12:13], v[12:13], 2, v[2:3]
	v_lshl_add_u64 v[14:15], v[14:15], 2, v[2:3]
	global_load_dword v6, v[6:7], off
	s_nop 0
	global_load_dword v7, v[8:9], off
	s_nop 0
	global_load_dword v8, v[10:11], off
	global_load_dword v9, v[12:13], off
	s_nop 0
	global_load_dword v10, v[14:15], off
	s_mov_b32 s1, 0x42ce8ed0
	s_mov_b32 s26, 0xc2b17218
	s_mul_i32 s21, s21, 12
	s_sub_i32 s4, s4, s21
	s_sext_i32_i8 s21, s4
	v_mov_b32_e32 v4, 0
	s_waitcnt vmcnt(7)
	v_mul_f32_e32 v11, 0xbfb8aa3b, v5
	s_waitcnt vmcnt(6)
	v_mul_f32_e32 v12, 0xbfb8aa3b, v16
	v_fma_f32 v14, v5, s35, -v11
	v_rndne_f32_e32 v15, v11
	s_waitcnt vmcnt(5)
	v_mul_f32_e32 v13, 0xbfb8aa3b, v17
	v_fma_f32 v18, v16, s35, -v12
	v_rndne_f32_e32 v19, v12
	v_fmac_f32_e32 v14, 0xb2a5705f, v5
	v_sub_f32_e32 v11, v11, v15
	v_fma_f32 v20, v17, s35, -v13
	v_rndne_f32_e32 v21, v13
	v_fmac_f32_e32 v18, 0xb2a5705f, v16
	v_sub_f32_e32 v12, v12, v19
	v_add_f32_e32 v11, v11, v14
	v_cvt_i32_f32_e32 v15, v15
	v_fmac_f32_e32 v20, 0xb2a5705f, v17
	v_sub_f32_e32 v13, v13, v21
	v_add_f32_e32 v12, v12, v18
	v_exp_f32_e32 v11, v11
	v_cvt_i32_f32_e32 v19, v19
	v_add_f32_e32 v13, v13, v20
	v_exp_f32_e32 v12, v12
	v_cvt_i32_f32_e32 v21, v21
	v_exp_f32_e32 v13, v13
	v_ldexp_f32 v11, v11, v15
	v_cmp_nlt_f32_e32 vcc, s1, v5
	v_ldexp_f32 v12, v12, v19
	v_ldexp_f32 v13, v13, v21
	v_cndmask_b32_e32 v11, 0, v11, vcc
	v_cmp_nlt_f32_e32 vcc, s1, v16
	s_nop 1
	v_cndmask_b32_e32 v12, 0, v12, vcc
	v_cmp_nlt_f32_e32 vcc, s1, v17
	s_nop 1
	v_cndmask_b32_e32 v13, 0, v13, vcc
	v_cmp_ngt_f32_e32 vcc, s26, v5
	s_nop 1
	v_cndmask_b32_e32 v11, v214, v11, vcc
	v_cmp_ngt_f32_e32 vcc, s26, v16
	v_add_f32_e32 v11, 1.0, v11
	v_div_scale_f32 v14, s[4:5], v11, v11, v5
	v_cndmask_b32_e32 v12, v214, v12, vcc
	v_add_f32_e32 v12, 1.0, v12
	v_rcp_f32_e32 v19, v14
	v_div_scale_f32 v18, s[4:5], v12, v12, v16
	v_rcp_f32_e32 v20, v18
	v_cmp_ngt_f32_e32 vcc, s26, v17
	v_fma_f32 v22, -v14, v19, 1.0
	v_fmac_f32_e32 v19, v22, v19
	v_cndmask_b32_e32 v13, v214, v13, vcc
	v_div_scale_f32 v15, vcc, v5, v11, v5
	v_fma_f32 v23, -v18, v20, 1.0
	v_mul_f32_e32 v22, v15, v19
	v_div_scale_f32 v21, s[4:5], v16, v12, v16
	v_fmac_f32_e32 v20, v23, v20
	v_fma_f32 v24, -v14, v22, v15
	v_mul_f32_e32 v23, v21, v20
	v_fmac_f32_e32 v22, v24, v19
	v_fma_f32 v25, -v18, v23, v21
	v_fma_f32 v14, -v14, v22, v15
	v_add_f32_e32 v13, 1.0, v13
	v_fmac_f32_e32 v23, v25, v20
	v_div_fmas_f32 v14, v14, v19, v22
	v_fma_f32 v15, -v18, v23, v21
	v_div_fixup_f32 v5, v14, v11, v5
	v_div_scale_f32 v11, s[24:25], v13, v13, v17
	s_mov_b64 vcc, s[4:5]
	v_rcp_f32_e32 v14, v11
	v_div_fmas_f32 v15, v15, v20, v23
	v_div_fixup_f32 v12, v15, v12, v16
	s_waitcnt vmcnt(4)
	v_mul_f32_e32 v15, 0xbfb8aa3b, v6
	v_fma_f32 v16, v6, s35, -v15
	v_rndne_f32_e32 v18, v15
	v_fmac_f32_e32 v16, 0xb2a5705f, v6
	v_sub_f32_e32 v15, v15, v18
	ds_write2st64_b32 v40, v5, v12 offset1:8
	v_fma_f32 v5, -v11, v14, 1.0
	v_add_f32_e32 v15, v15, v16
	v_fmac_f32_e32 v14, v5, v14
	v_div_scale_f32 v5, vcc, v17, v13, v17
	v_exp_f32_e32 v15, v15
	v_cvt_i32_f32_e32 v16, v18
	v_mul_f32_e32 v12, v5, v14
	v_fma_f32 v18, -v11, v12, v5
	v_fmac_f32_e32 v12, v18, v14
	v_fma_f32 v5, -v11, v12, v5
	v_ldexp_f32 v11, v15, v16
	v_cmp_nlt_f32_e64 s[4:5], s1, v6
	v_div_fmas_f32 v5, v5, v14, v12
	s_waitcnt vmcnt(3)
	v_mul_f32_e32 v14, 0xbfb8aa3b, v7
	v_cndmask_b32_e64 v11, 0, v11, s[4:5]
	v_cmp_ngt_f32_e64 s[4:5], s26, v6
	v_div_fixup_f32 v5, v5, v13, v17
	v_fma_f32 v17, v7, s35, -v14
	v_cndmask_b32_e64 v11, v214, v11, s[4:5]
	v_add_f32_e32 v11, 1.0, v11
	v_div_scale_f32 v15, s[4:5], v11, v11, v6
	v_rcp_f32_e32 v16, v15
	v_rndne_f32_e32 v18, v14
	v_fmac_f32_e32 v17, 0xb2a5705f, v7
	v_sub_f32_e32 v14, v14, v18
	v_fma_f32 v12, -v15, v16, 1.0
	v_fmac_f32_e32 v16, v12, v16
	v_div_scale_f32 v12, vcc, v6, v11, v6
	v_add_f32_e32 v14, v14, v17
	v_mul_f32_e32 v13, v12, v16
	v_exp_f32_e32 v14, v14
	v_cvt_i32_f32_e32 v17, v18
	v_fma_f32 v18, -v15, v13, v12
	v_fmac_f32_e32 v13, v18, v16
	v_fma_f32 v12, -v15, v13, v12
	v_ldexp_f32 v14, v14, v17
	v_cmp_nlt_f32_e64 s[4:5], s1, v7
	v_div_fmas_f32 v12, v12, v16, v13
	v_div_fixup_f32 v6, v12, v11, v6
	v_cndmask_b32_e64 v14, 0, v14, s[4:5]
	v_cmp_ngt_f32_e64 s[4:5], s26, v7
	s_waitcnt vmcnt(2)
; __device__ __forceinline__ void mod_item(const int tid, float* cs, const Params& p, int item) {
;     ...
;     for (int i = 0; i < 8; ++i) { const int idx = tid + 512 * i, r = idx & 15, k = idx >> 4;
;         const float x = (r < 8 ? p.in[2] + r * 2048 : p.in[3] + (r - 8) * 2048)[k0 + k]; cs[idx] = x / (1.f + expf(-x)); }
;     __syncthreads();
;     float acc[16];
; #pragma unroll
;     for (int r = 0; r < 16; ++r) acc[r] = 0.f;
;     const float* w = p.in[9] + (size_t)l * 2048 * 6144 + (size_t)k0 * 6144 + col;
; #pragma unroll 8
;     for (int k = 0; k < 256; ++k) {
;         const float wv = w[(size_t)k * 6144];
;         const f32x4 c0 = *(const f32x4*)(cs + k * 16), c1 = *(const f32x4*)(cs + k * 16 + 4), c2 = *(const f32x4*)(cs + k * 16 + 8), c3 = *(const f32x4*)(cs + k * 16 + 12);
	v_mul_f32_e32 v11, 0xbfb8aa3b, v8
	v_fma_f32 v12, v8, s35, -v11
	v_cndmask_b32_e64 v14, v214, v14, s[4:5]
	v_rndne_f32_e32 v13, v11
	v_add_f32_e32 v14, 1.0, v14
	v_fmac_f32_e32 v12, 0xb2a5705f, v8
	v_sub_f32_e32 v11, v11, v13
	v_div_scale_f32 v15, s[4:5], v14, v14, v7
	v_add_f32_e32 v11, v11, v12
	v_rcp_f32_e32 v17, v15
	v_exp_f32_e32 v11, v11
	v_cvt_i32_f32_e32 v12, v13
	ds_write2st64_b32 v40, v5, v6 offset0:16 offset1:24
	v_fma_f32 v5, -v15, v17, 1.0
	v_cmp_nlt_f32_e64 s[4:5], s1, v8
	v_ldexp_f32 v11, v11, v12
	v_fmac_f32_e32 v17, v5, v17
	v_div_scale_f32 v5, vcc, v7, v14, v7
	v_cndmask_b32_e64 v11, 0, v11, s[4:5]
	v_cmp_ngt_f32_e64 s[4:5], s26, v8
	v_mul_f32_e32 v6, v5, v17
	v_fma_f32 v13, -v15, v6, v5
	v_cndmask_b32_e64 v11, v214, v11, s[4:5]
	v_add_f32_e32 v11, 1.0, v11
	v_fmac_f32_e32 v6, v13, v17
	v_div_scale_f32 v12, s[4:5], v11, v11, v8
	v_fma_f32 v5, -v15, v6, v5
	v_rcp_f32_e32 v13, v12
	v_div_fmas_f32 v5, v5, v17, v6
	v_div_fixup_f32 v5, v5, v14, v7
	s_waitcnt vmcnt(1)
	v_mul_f32_e32 v14, 0xbfb8aa3b, v9
	v_fma_f32 v15, v9, s35, -v14
	v_rndne_f32_e32 v16, v14
	v_fma_f32 v6, -v12, v13, 1.0
	v_fmac_f32_e32 v15, 0xb2a5705f, v9
	v_sub_f32_e32 v14, v14, v16
	v_fmac_f32_e32 v13, v6, v13
	v_div_scale_f32 v6, vcc, v8, v11, v8
	v_add_f32_e32 v14, v14, v15
	v_mul_f32_e32 v7, v6, v13
	v_exp_f32_e32 v14, v14
	v_cvt_i32_f32_e32 v15, v16
	v_fma_f32 v16, -v12, v7, v6
	v_fmac_f32_e32 v7, v16, v13
	v_fma_f32 v6, -v12, v7, v6
	v_ldexp_f32 v12, v14, v15
	v_cmp_nlt_f32_e64 s[4:5], s1, v9
	v_div_fmas_f32 v6, v6, v13, v7
	s_waitcnt vmcnt(0)
	v_mul_f32_e32 v7, 0xbfb8aa3b, v10
	v_cndmask_b32_e64 v12, 0, v12, s[4:5]
	v_cmp_ngt_f32_e64 s[4:5], s26, v9
	v_div_fixup_f32 v6, v6, v11, v8
	v_fma_f32 v8, v10, s35, -v7
	v_rndne_f32_e32 v11, v7
	v_cndmask_b32_e64 v12, v214, v12, s[4:5]
	v_fmac_f32_e32 v8, 0xb2a5705f, v10
	v_sub_f32_e32 v7, v7, v11
	v_add_f32_e32 v12, 1.0, v12
	v_add_f32_e32 v7, v7, v8
	v_div_scale_f32 v14, s[4:5], v12, v12, v9
	v_exp_f32_e32 v7, v7
	v_cvt_i32_f32_e32 v8, v11
	v_rcp_f32_e32 v15, v14
	v_cmp_nlt_f32_e64 s[4:5], s1, v10
	ds_write2st64_b32 v40, v5, v6 offset0:32 offset1:40
	v_ldexp_f32 v7, v7, v8
	v_fma_f32 v5, -v14, v15, 1.0
	v_cndmask_b32_e64 v7, 0, v7, s[4:5]
	v_cmp_ngt_f32_e64 s[4:5], s26, v10
	v_fmac_f32_e32 v15, v5, v15
	v_div_scale_f32 v5, vcc, v9, v12, v9
	v_cndmask_b32_e64 v7, v214, v7, s[4:5]
	v_mul_f32_e32 v6, v5, v15
	v_add_f32_e32 v7, 1.0, v7
	v_fma_f32 v11, -v14, v6, v5
	v_div_scale_f32 v8, s[4:5], v7, v7, v10
	v_fmac_f32_e32 v6, v11, v15
	v_rcp_f32_e32 v11, v8
	v_fma_f32 v5, -v14, v6, v5
	v_div_fmas_f32 v5, v5, v15, v6
	v_div_fixup_f32 v5, v5, v12, v9
	v_fma_f32 v6, -v8, v11, 1.0
	v_fmac_f32_e32 v11, v6, v11
	v_div_scale_f32 v6, vcc, v10, v7, v10
	v_mul_f32_e32 v9, v6, v11
	v_fma_f32 v12, -v8, v9, v6
	v_fmac_f32_e32 v9, v12, v11
	v_fma_f32 v6, -v8, v9, v6
	v_div_fmas_f32 v6, v6, v11, v9
	v_readlane_b32 s24, v246, 54
	v_div_fixup_f32 v6, v6, v7, v10
	s_mul_i32 s5, s14, 0x3000000
	v_readlane_b32 s26, v246, 56
	ds_write2st64_b32 v40, v5, v6 offset0:48 offset1:56
	v_lshl_add_u32 v6, s21, 9, v188
	s_mul_hi_i32 s4, s14, 0x3000000
	v_readlane_b32 s27, v246, 57
	s_add_u32 s21, s26, s5
	s_addc_u32 s24, s27, s4
	s_mul_i32 s4, s15, 0x180000
	s_ashr_i32 s5, s4, 31
	s_lshl_b64 s[4:5], s[4:5], 2
	s_add_u32 s4, s21, s4
	s_addc_u32 s5, s24, s5
	v_ashrrev_i32_e32 v7, 31, v6
	v_lshl_add_u64 v[8:9], v[6:7], 2, s[4:5]
	s_mov_b32 s21, 0
	s_mov_b64 s[4:5], 0
	v_mov_b32_e32 v5, v4
	v_mov_b32_e32 v24, v4
	v_mov_b32_e32 v25, v4
	v_mov_b32_e32 v22, v4
	v_mov_b32_e32 v23, v4
	v_mov_b32_e32 v18, v4
	v_mov_b32_e32 v19, v4
	v_mov_b32_e32 v16, v4
	v_mov_b32_e32 v17, v4
	v_mov_b32_e32 v14, v4
	v_mov_b32_e32 v15, v4
	v_mov_b32_e32 v12, v4
	v_mov_b32_e32 v13, v4
	v_mov_b32_e32 v10, v4
	v_mov_b32_e32 v11, v4
	s_waitcnt lgkmcnt(0)
	s_barrier
	v_readlane_b32 s25, v246, 55
	v_readlane_b32 s28, v246, 58
	v_readlane_b32 s29, v246, 59
	v_readlane_b32 s30, v246, 60
	v_readlane_b32 s31, v246, 61
	s_mov_b64 s[4:5], 0x6000
	v_mov_b64_e32 v[20:21], v[8:9]
	v_mov_b32_e32 v48, 0
	global_load_dword v64, v[20:21], off
	v_lshl_add_u64 v[20:21], v[20:21], 0, s[4:5]
	global_load_dword v65, v[20:21], off
	v_lshl_add_u64 v[20:21], v[20:21], 0, s[4:5]
	global_load_dword v66, v[20:21], off
	v_lshl_add_u64 v[20:21], v[20:21], 0, s[4:5]
	global_load_dword v67, v[20:21], off
	v_lshl_add_u64 v[20:21], v[20:21], 0, s[4:5]
	global_load_dword v68, v[20:21], off
	v_lshl_add_u64 v[20:21], v[20:21], 0, s[4:5]
	global_load_dword v69, v[20:21], off
	v_lshl_add_u64 v[20:21], v[20:21], 0, s[4:5]
	global_load_dword v70, v[20:21], off
	v_lshl_add_u64 v[20:21], v[20:21], 0, s[4:5]
	global_load_dword v71, v[20:21], off
	v_lshl_add_u64 v[20:21], v[20:21], 0, s[4:5]
	global_load_dword v72, v[20:21], off
	v_lshl_add_u64 v[20:21], v[20:21], 0, s[4:5]
	global_load_dword v73, v[20:21], off
	v_lshl_add_u64 v[20:21], v[20:21], 0, s[4:5]
	global_load_dword v74, v[20:21], off
	v_lshl_add_u64 v[20:21], v[20:21], 0, s[4:5]
	global_load_dword v75, v[20:21], off
	v_lshl_add_u64 v[20:21], v[20:21], 0, s[4:5]
	global_load_dword v76, v[20:21], off
	v_lshl_add_u64 v[20:21], v[20:21], 0, s[4:5]
	global_load_dword v77, v[20:21], off
	v_lshl_add_u64 v[20:21], v[20:21], 0, s[4:5]
	global_load_dword v78, v[20:21], off
	v_lshl_add_u64 v[20:21], v[20:21], 0, s[4:5]
	global_load_dword v79, v[20:21], off
	v_lshl_add_u64 v[20:21], v[20:21], 0, s[4:5]
	global_load_dword v80, v[20:21], off
	v_lshl_add_u64 v[20:21], v[20:21], 0, s[4:5]
	global_load_dword v81, v[20:21], off
	v_lshl_add_u64 v[20:21], v[20:21], 0, s[4:5]
	global_load_dword v82, v[20:21], off
	v_lshl_add_u64 v[20:21], v[20:21], 0, s[4:5]
	global_load_dword v83, v[20:21], off
	v_lshl_add_u64 v[20:21], v[20:21], 0, s[4:5]
	global_load_dword v84, v[20:21], off
	v_lshl_add_u64 v[20:21], v[20:21], 0, s[4:5]
	global_load_dword v85, v[20:21], off
	v_lshl_add_u64 v[20:21], v[20:21], 0, s[4:5]
	global_load_dword v86, v[20:21], off
	v_lshl_add_u64 v[20:21], v[20:21], 0, s[4:5]
	global_load_dword v87, v[20:21], off
	v_lshl_add_u64 v[20:21], v[20:21], 0, s[4:5]
	global_load_dword v88, v[20:21], off
	v_lshl_add_u64 v[20:21], v[20:21], 0, s[4:5]
	global_load_dword v89, v[20:21], off
	v_lshl_add_u64 v[20:21], v[20:21], 0, s[4:5]
	global_load_dword v90, v[20:21], off
	v_lshl_add_u64 v[20:21], v[20:21], 0, s[4:5]
	global_load_dword v91, v[20:21], off
	v_lshl_add_u64 v[20:21], v[20:21], 0, s[4:5]
	global_load_dword v92, v[20:21], off
	v_lshl_add_u64 v[20:21], v[20:21], 0, s[4:5]
	global_load_dword v93, v[20:21], off
	v_lshl_add_u64 v[20:21], v[20:21], 0, s[4:5]
	global_load_dword v94, v[20:21], off
	v_lshl_add_u64 v[20:21], v[20:21], 0, s[4:5]
	global_load_dword v95, v[20:21], off
	v_lshl_add_u64 v[20:21], v[20:21], 0, s[4:5]
	ds_read_b128 v[100:103], v48 offset:0
	ds_read_b128 v[104:107], v48 offset:16
	ds_read_b128 v[108:111], v48 offset:32
	ds_read_b128 v[112:115], v48 offset:48
	s_mov_b32 s21, 7
; __device__ __forceinline__ void mod_item(const int tid, float* cs, const Params& p, int item) {
;     ...
; #pragma unroll 8
;     for (int k = 0; k < 256; ++k) {
;         const float wv = w[(size_t)k * 6144];
;         const f32x4 c0 = *(const f32x4*)(cs + k * 16), c1 = *(const f32x4*)(cs + k * 16 + 4), c2 = *(const f32x4*)(cs + k * 16 + 8), c3 = *(const f32x4*)(cs + k * 16 + 12);
; #pragma unroll
;         for (int j = 0; j < 4; ++j) { acc[j] += wv * c0[j]; acc[4 + j] += wv * c1[j]; acc[8 + j] += wv * c2[j]; acc[12 + j] += wv * c3[j]; }
;     }
.Lmod_loop:
	ds_read_b128 v[116:119], v48 offset:64
	ds_read_b128 v[120:123], v48 offset:80
	ds_read_b128 v[124:127], v48 offset:96
	ds_read_b128 v[128:131], v48 offset:112
	s_waitcnt lgkmcnt(4)
	s_waitcnt vmcnt(31)
	v_pk_fma_f32 v[24:25], v[64:65], v[100:101], v[24:25] op_sel_hi:[0,1,1]
	v_pk_fma_f32 v[22:23], v[64:65], v[102:103], v[22:23] op_sel_hi:[0,1,1]
	v_pk_fma_f32 v[18:19], v[64:65], v[104:105], v[18:19] op_sel_hi:[0,1,1]
	v_pk_fma_f32 v[16:17], v[64:65], v[106:107], v[16:17] op_sel_hi:[0,1,1]
	v_pk_fma_f32 v[14:15], v[64:65], v[108:109], v[14:15] op_sel_hi:[0,1,1]
	v_pk_fma_f32 v[12:13], v[64:65], v[110:111], v[12:13] op_sel_hi:[0,1,1]
	v_pk_fma_f32 v[10:11], v[64:65], v[112:113], v[10:11] op_sel_hi:[0,1,1]
	v_pk_fma_f32 v[4:5], v[64:65], v[114:115], v[4:5] op_sel_hi:[0,1,1]
	global_load_dword v64, v[20:21], off
	v_lshl_add_u64 v[20:21], v[20:21], 0, s[4:5]
	ds_read_b128 v[100:103], v48 offset:128
	ds_read_b128 v[104:107], v48 offset:144
	ds_read_b128 v[108:111], v48 offset:160
	ds_read_b128 v[112:115], v48 offset:176
	s_waitcnt lgkmcnt(4)
	s_waitcnt vmcnt(31)
	v_pk_fma_f32 v[24:25], v[64:65], v[116:117], v[24:25] op_sel:[1,0,0] op_sel_hi:[1,1,1]
	v_pk_fma_f32 v[22:23], v[64:65], v[118:119], v[22:23] op_sel:[1,0,0] op_sel_hi:[1,1,1]
	v_pk_fma_f32 v[18:19], v[64:65], v[120:121], v[18:19] op_sel:[1,0,0] op_sel_hi:[1,1,1]
	v_pk_fma_f32 v[16:17], v[64:65], v[122:123], v[16:17] op_sel:[1,0,0] op_sel_hi:[1,1,1]
	v_pk_fma_f32 v[14:15], v[64:65], v[124:125], v[14:15] op_sel:[1,0,0] op_sel_hi:[1,1,1]
	v_pk_fma_f32 v[12:13], v[64:65], v[126:127], v[12:13] op_sel:[1,0,0] op_sel_hi:[1,1,1]
	v_pk_fma_f32 v[10:11], v[64:65], v[128:129], v[10:11] op_sel:[1,0,0] op_sel_hi:[1,1,1]
	v_pk_fma_f32 v[4:5], v[64:65], v[130:131], v[4:5] op_sel:[1,0,0] op_sel_hi:[1,1,1]
	global_load_dword v65, v[20:21], off
	v_lshl_add_u64 v[20:21], v[20:21], 0, s[4:5]
	ds_read_b128 v[116:119], v48 offset:192
	ds_read_b128 v[120:123], v48 offset:208
	ds_read_b128 v[124:127], v48 offset:224
	ds_read_b128 v[128:131], v48 offset:240
	s_waitcnt lgkmcnt(4)
	s_waitcnt vmcnt(31)
	v_pk_fma_f32 v[24:25], v[66:67], v[100:101], v[24:25] op_sel_hi:[0,1,1]
	v_pk_fma_f32 v[22:23], v[66:67], v[102:103], v[22:23] op_sel_hi:[0,1,1]
	v_pk_fma_f32 v[18:19], v[66:67], v[104:105], v[18:19] op_sel_hi:[0,1,1]
	v_pk_fma_f32 v[16:17], v[66:67], v[106:107], v[16:17] op_sel_hi:[0,1,1]
	v_pk_fma_f32 v[14:15], v[66:67], v[108:109], v[14:15] op_sel_hi:[0,1,1]
	v_pk_fma_f32 v[12:13], v[66:67], v[110:111], v[12:13] op_sel_hi:[0,1,1]
	v_pk_fma_f32 v[10:11], v[66:67], v[112:113], v[10:11] op_sel_hi:[0,1,1]
	v_pk_fma_f32 v[4:5], v[66:67], v[114:115], v[4:5] op_sel_hi:[0,1,1]
	global_load_dword v66, v[20:21], off
	v_lshl_add_u64 v[20:21], v[20:21], 0, s[4:5]
	ds_read_b128 v[100:103], v48 offset:256
	ds_read_b128 v[104:107], v48 offset:272
	ds_read_b128 v[108:111], v48 offset:288
	ds_read_b128 v[112:115], v48 offset:304
	s_waitcnt lgkmcnt(4)
	s_waitcnt vmcnt(31)
	v_pk_fma_f32 v[24:25], v[66:67], v[116:117], v[24:25] op_sel:[1,0,0] op_sel_hi:[1,1,1]
	v_pk_fma_f32 v[22:23], v[66:67], v[118:119], v[22:23] op_sel:[1,0,0] op_sel_hi:[1,1,1]
	v_pk_fma_f32 v[18:19], v[66:67], v[120:121], v[18:19] op_sel:[1,0,0] op_sel_hi:[1,1,1]
	v_pk_fma_f32 v[16:17], v[66:67], v[122:123], v[16:17] op_sel:[1,0,0] op_sel_hi:[1,1,1]
	v_pk_fma_f32 v[14:15], v[66:67], v[124:125], v[14:15] op_sel:[1,0,0] op_sel_hi:[1,1,1]
	v_pk_fma_f32 v[12:13], v[66:67], v[126:127], v[12:13] op_sel:[1,0,0] op_sel_hi:[1,1,1]
	v_pk_fma_f32 v[10:11], v[66:67], v[128:129], v[10:11] op_sel:[1,0,0] op_sel_hi:[1,1,1]
	v_pk_fma_f32 v[4:5], v[66:67], v[130:131], v[4:5] op_sel:[1,0,0] op_sel_hi:[1,1,1]
	global_load_dword v67, v[20:21], off
	v_lshl_add_u64 v[20:21], v[20:21], 0, s[4:5]
	ds_read_b128 v[116:119], v48 offset:320
	ds_read_b128 v[120:123], v48 offset:336
	ds_read_b128 v[124:127], v48 offset:352
	ds_read_b128 v[128:131], v48 offset:368
	s_waitcnt lgkmcnt(4)
	s_waitcnt vmcnt(31)
	v_pk_fma_f32 v[24:25], v[68:69], v[100:101], v[24:25] op_sel_hi:[0,1,1]
	v_pk_fma_f32 v[22:23], v[68:69], v[102:103], v[22:23] op_sel_hi:[0,1,1]
	v_pk_fma_f32 v[18:19], v[68:69], v[104:105], v[18:19] op_sel_hi:[0,1,1]
	v_pk_fma_f32 v[16:17], v[68:69], v[106:107], v[16:17] op_sel_hi:[0,1,1]
	v_pk_fma_f32 v[14:15], v[68:69], v[108:109], v[14:15] op_sel_hi:[0,1,1]
	v_pk_fma_f32 v[12:13], v[68:69], v[110:111], v[12:13] op_sel_hi:[0,1,1]
	v_pk_fma_f32 v[10:11], v[68:69], v[112:113], v[10:11] op_sel_hi:[0,1,1]
	v_pk_fma_f32 v[4:5], v[68:69], v[114:115], v[4:5] op_sel_hi:[0,1,1]
	global_load_dword v68, v[20:21], off
	v_lshl_add_u64 v[20:21], v[20:21], 0, s[4:5]
	ds_read_b128 v[100:103], v48 offset:384
	ds_read_b128 v[104:107], v48 offset:400
	ds_read_b128 v[108:111], v48 offset:416
	ds_read_b128 v[112:115], v48 offset:432
	s_waitcnt lgkmcnt(4)
	s_waitcnt vmcnt(31)
	v_pk_fma_f32 v[24:25], v[68:69], v[116:117], v[24:25] op_sel:[1,0,0] op_sel_hi:[1,1,1]
	v_pk_fma_f32 v[22:23], v[68:69], v[118:119], v[22:23] op_sel:[1,0,0] op_sel_hi:[1,1,1]
	v_pk_fma_f32 v[18:19], v[68:69], v[120:121], v[18:19] op_sel:[1,0,0] op_sel_hi:[1,1,1]
	v_pk_fma_f32 v[16:17], v[68:69], v[122:123], v[16:17] op_sel:[1,0,0] op_sel_hi:[1,1,1]
	v_pk_fma_f32 v[14:15], v[68:69], v[124:125], v[14:15] op_sel:[1,0,0] op_sel_hi:[1,1,1]
	v_pk_fma_f32 v[12:13], v[68:69], v[126:127], v[12:13] op_sel:[1,0,0] op_sel_hi:[1,1,1]
	v_pk_fma_f32 v[10:11], v[68:69], v[128:129], v[10:11] op_sel:[1,0,0] op_sel_hi:[1,1,1]
	v_pk_fma_f32 v[4:5], v[68:69], v[130:131], v[4:5] op_sel:[1,0,0] op_sel_hi:[1,1,1]
	global_load_dword v69, v[20:21], off
	v_lshl_add_u64 v[20:21], v[20:21], 0, s[4:5]
	ds_read_b128 v[116:119], v48 offset:448
	ds_read_b128 v[120:123], v48 offset:464
	ds_read_b128 v[124:127], v48 offset:480
	ds_read_b128 v[128:131], v48 offset:496
	s_waitcnt lgkmcnt(4)
; __device__ __forceinline__ void mod_item(const int tid, float* cs, const Params& p, int item) {
;     ...
; #pragma unroll 8
;     for (int k = 0; k < 256; ++k) {
;         const float wv = w[(size_t)k * 6144];
;         const f32x4 c0 = *(const f32x4*)(cs + k * 16), c1 = *(const f32x4*)(cs + k * 16 + 4), c2 = *(const f32x4*)(cs + k * 16 + 8), c3 = *(const f32x4*)(cs + k * 16 + 12);
; #pragma unroll
;         for (int j = 0; j < 4; ++j) { acc[j] += wv * c0[j]; acc[4 + j] += wv * c1[j]; acc[8 + j] += wv * c2[j]; acc[12 + j] += wv * c3[j]; }
;     }
	s_waitcnt vmcnt(31)
	v_pk_fma_f32 v[24:25], v[70:71], v[100:101], v[24:25] op_sel_hi:[0,1,1]
	v_pk_fma_f32 v[22:23], v[70:71], v[102:103], v[22:23] op_sel_hi:[0,1,1]
	v_pk_fma_f32 v[18:19], v[70:71], v[104:105], v[18:19] op_sel_hi:[0,1,1]
	v_pk_fma_f32 v[16:17], v[70:71], v[106:107], v[16:17] op_sel_hi:[0,1,1]
	v_pk_fma_f32 v[14:15], v[70:71], v[108:109], v[14:15] op_sel_hi:[0,1,1]
	v_pk_fma_f32 v[12:13], v[70:71], v[110:111], v[12:13] op_sel_hi:[0,1,1]
	v_pk_fma_f32 v[10:11], v[70:71], v[112:113], v[10:11] op_sel_hi:[0,1,1]
	v_pk_fma_f32 v[4:5], v[70:71], v[114:115], v[4:5] op_sel_hi:[0,1,1]
	global_load_dword v70, v[20:21], off
	v_lshl_add_u64 v[20:21], v[20:21], 0, s[4:5]
	ds_read_b128 v[100:103], v48 offset:512
	ds_read_b128 v[104:107], v48 offset:528
	ds_read_b128 v[108:111], v48 offset:544
	ds_read_b128 v[112:115], v48 offset:560
	s_waitcnt lgkmcnt(4)
	s_waitcnt vmcnt(31)
	v_pk_fma_f32 v[24:25], v[70:71], v[116:117], v[24:25] op_sel:[1,0,0] op_sel_hi:[1,1,1]
	v_pk_fma_f32 v[22:23], v[70:71], v[118:119], v[22:23] op_sel:[1,0,0] op_sel_hi:[1,1,1]
	v_pk_fma_f32 v[18:19], v[70:71], v[120:121], v[18:19] op_sel:[1,0,0] op_sel_hi:[1,1,1]
	v_pk_fma_f32 v[16:17], v[70:71], v[122:123], v[16:17] op_sel:[1,0,0] op_sel_hi:[1,1,1]
	v_pk_fma_f32 v[14:15], v[70:71], v[124:125], v[14:15] op_sel:[1,0,0] op_sel_hi:[1,1,1]
	v_pk_fma_f32 v[12:13], v[70:71], v[126:127], v[12:13] op_sel:[1,0,0] op_sel_hi:[1,1,1]
	v_pk_fma_f32 v[10:11], v[70:71], v[128:129], v[10:11] op_sel:[1,0,0] op_sel_hi:[1,1,1]
	v_pk_fma_f32 v[4:5], v[70:71], v[130:131], v[4:5] op_sel:[1,0,0] op_sel_hi:[1,1,1]
	global_load_dword v71, v[20:21], off
	v_lshl_add_u64 v[20:21], v[20:21], 0, s[4:5]
	ds_read_b128 v[116:119], v48 offset:576
	ds_read_b128 v[120:123], v48 offset:592
	ds_read_b128 v[124:127], v48 offset:608
	ds_read_b128 v[128:131], v48 offset:624
	s_waitcnt lgkmcnt(4)
	s_waitcnt vmcnt(31)
	v_pk_fma_f32 v[24:25], v[72:73], v[100:101], v[24:25] op_sel_hi:[0,1,1]
	v_pk_fma_f32 v[22:23], v[72:73], v[102:103], v[22:23] op_sel_hi:[0,1,1]
	v_pk_fma_f32 v[18:19], v[72:73], v[104:105], v[18:19] op_sel_hi:[0,1,1]
	v_pk_fma_f32 v[16:17], v[72:73], v[106:107], v[16:17] op_sel_hi:[0,1,1]
	v_pk_fma_f32 v[14:15], v[72:73], v[108:109], v[14:15] op_sel_hi:[0,1,1]
	v_pk_fma_f32 v[12:13], v[72:73], v[110:111], v[12:13] op_sel_hi:[0,1,1]
	v_pk_fma_f32 v[10:11], v[72:73], v[112:113], v[10:11] op_sel_hi:[0,1,1]
	v_pk_fma_f32 v[4:5], v[72:73], v[114:115], v[4:5] op_sel_hi:[0,1,1]
	global_load_dword v72, v[20:21], off
	v_lshl_add_u64 v[20:21], v[20:21], 0, s[4:5]
	ds_read_b128 v[100:103], v48 offset:640
	ds_read_b128 v[104:107], v48 offset:656
	ds_read_b128 v[108:111], v48 offset:672
	ds_read_b128 v[112:115], v48 offset:688
	s_waitcnt lgkmcnt(4)
	s_waitcnt vmcnt(31)
	v_pk_fma_f32 v[24:25], v[72:73], v[116:117], v[24:25] op_sel:[1,0,0] op_sel_hi:[1,1,1]
	v_pk_fma_f32 v[22:23], v[72:73], v[118:119], v[22:23] op_sel:[1,0,0] op_sel_hi:[1,1,1]
	v_pk_fma_f32 v[18:19], v[72:73], v[120:121], v[18:19] op_sel:[1,0,0] op_sel_hi:[1,1,1]
	v_pk_fma_f32 v[16:17], v[72:73], v[122:123], v[16:17] op_sel:[1,0,0] op_sel_hi:[1,1,1]
	v_pk_fma_f32 v[14:15], v[72:73], v[124:125], v[14:15] op_sel:[1,0,0] op_sel_hi:[1,1,1]
	v_pk_fma_f32 v[12:13], v[72:73], v[126:127], v[12:13] op_sel:[1,0,0] op_sel_hi:[1,1,1]
	v_pk_fma_f32 v[10:11], v[72:73], v[128:129], v[10:11] op_sel:[1,0,0] op_sel_hi:[1,1,1]
	v_pk_fma_f32 v[4:5], v[72:73], v[130:131], v[4:5] op_sel:[1,0,0] op_sel_hi:[1,1,1]
	global_load_dword v73, v[20:21], off
	v_lshl_add_u64 v[20:21], v[20:21], 0, s[4:5]
	ds_read_b128 v[116:119], v48 offset:704
	ds_read_b128 v[120:123], v48 offset:720
	ds_read_b128 v[124:127], v48 offset:736
	ds_read_b128 v[128:131], v48 offset:752
	s_waitcnt lgkmcnt(4)
	s_waitcnt vmcnt(31)
	v_pk_fma_f32 v[24:25], v[74:75], v[100:101], v[24:25] op_sel_hi:[0,1,1]
	v_pk_fma_f32 v[22:23], v[74:75], v[102:103], v[22:23] op_sel_hi:[0,1,1]
	v_pk_fma_f32 v[18:19], v[74:75], v[104:105], v[18:19] op_sel_hi:[0,1,1]
	v_pk_fma_f32 v[16:17], v[74:75], v[106:107], v[16:17] op_sel_hi:[0,1,1]
	v_pk_fma_f32 v[14:15], v[74:75], v[108:109], v[14:15] op_sel_hi:[0,1,1]
	v_pk_fma_f32 v[12:13], v[74:75], v[110:111], v[12:13] op_sel_hi:[0,1,1]
	v_pk_fma_f32 v[10:11], v[74:75], v[112:113], v[10:11] op_sel_hi:[0,1,1]
	v_pk_fma_f32 v[4:5], v[74:75], v[114:115], v[4:5] op_sel_hi:[0,1,1]
	global_load_dword v74, v[20:21], off
	v_lshl_add_u64 v[20:21], v[20:21], 0, s[4:5]
	ds_read_b128 v[100:103], v48 offset:768
	ds_read_b128 v[104:107], v48 offset:784
	ds_read_b128 v[108:111], v48 offset:800
	ds_read_b128 v[112:115], v48 offset:816
	s_waitcnt lgkmcnt(4)
	s_waitcnt vmcnt(31)
	v_pk_fma_f32 v[24:25], v[74:75], v[116:117], v[24:25] op_sel:[1,0,0] op_sel_hi:[1,1,1]
	v_pk_fma_f32 v[22:23], v[74:75], v[118:119], v[22:23] op_sel:[1,0,0] op_sel_hi:[1,1,1]
	v_pk_fma_f32 v[18:19], v[74:75], v[120:121], v[18:19] op_sel:[1,0,0] op_sel_hi:[1,1,1]
	v_pk_fma_f32 v[16:17], v[74:75], v[122:123], v[16:17] op_sel:[1,0,0] op_sel_hi:[1,1,1]
	v_pk_fma_f32 v[14:15], v[74:75], v[124:125], v[14:15] op_sel:[1,0,0] op_sel_hi:[1,1,1]
	v_pk_fma_f32 v[12:13], v[74:75], v[126:127], v[12:13] op_sel:[1,0,0] op_sel_hi:[1,1,1]
	v_pk_fma_f32 v[10:11], v[74:75], v[128:129], v[10:11] op_sel:[1,0,0] op_sel_hi:[1,1,1]
	v_pk_fma_f32 v[4:5], v[74:75], v[130:131], v[4:5] op_sel:[1,0,0] op_sel_hi:[1,1,1]
	global_load_dword v75, v[20:21], off
	v_lshl_add_u64 v[20:21], v[20:21], 0, s[4:5]
	ds_read_b128 v[116:119], v48 offset:832
	ds_read_b128 v[120:123], v48 offset:848
	ds_read_b128 v[124:127], v48 offset:864
	ds_read_b128 v[128:131], v48 offset:880
	s_waitcnt lgkmcnt(4)
	s_waitcnt vmcnt(31)
; __device__ __forceinline__ void mod_item(const int tid, float* cs, const Params& p, int item) {
;     ...
; #pragma unroll 8
;     for (int k = 0; k < 256; ++k) {
;         const float wv = w[(size_t)k * 6144];
;         const f32x4 c0 = *(const f32x4*)(cs + k * 16), c1 = *(const f32x4*)(cs + k * 16 + 4), c2 = *(const f32x4*)(cs + k * 16 + 8), c3 = *(const f32x4*)(cs + k * 16 + 12);
; #pragma unroll
;         for (int j = 0; j < 4; ++j) { acc[j] += wv * c0[j]; acc[4 + j] += wv * c1[j]; acc[8 + j] += wv * c2[j]; acc[12 + j] += wv * c3[j]; }
;     }
	v_pk_fma_f32 v[24:25], v[76:77], v[100:101], v[24:25] op_sel_hi:[0,1,1]
	v_pk_fma_f32 v[22:23], v[76:77], v[102:103], v[22:23] op_sel_hi:[0,1,1]
	v_pk_fma_f32 v[18:19], v[76:77], v[104:105], v[18:19] op_sel_hi:[0,1,1]
	v_pk_fma_f32 v[16:17], v[76:77], v[106:107], v[16:17] op_sel_hi:[0,1,1]
	v_pk_fma_f32 v[14:15], v[76:77], v[108:109], v[14:15] op_sel_hi:[0,1,1]
	v_pk_fma_f32 v[12:13], v[76:77], v[110:111], v[12:13] op_sel_hi:[0,1,1]
	v_pk_fma_f32 v[10:11], v[76:77], v[112:113], v[10:11] op_sel_hi:[0,1,1]
	v_pk_fma_f32 v[4:5], v[76:77], v[114:115], v[4:5] op_sel_hi:[0,1,1]
	global_load_dword v76, v[20:21], off
	v_lshl_add_u64 v[20:21], v[20:21], 0, s[4:5]
	ds_read_b128 v[100:103], v48 offset:896
	ds_read_b128 v[104:107], v48 offset:912
	ds_read_b128 v[108:111], v48 offset:928
	ds_read_b128 v[112:115], v48 offset:944
	s_waitcnt lgkmcnt(4)
	s_waitcnt vmcnt(31)
	v_pk_fma_f32 v[24:25], v[76:77], v[116:117], v[24:25] op_sel:[1,0,0] op_sel_hi:[1,1,1]
	v_pk_fma_f32 v[22:23], v[76:77], v[118:119], v[22:23] op_sel:[1,0,0] op_sel_hi:[1,1,1]
	v_pk_fma_f32 v[18:19], v[76:77], v[120:121], v[18:19] op_sel:[1,0,0] op_sel_hi:[1,1,1]
	v_pk_fma_f32 v[16:17], v[76:77], v[122:123], v[16:17] op_sel:[1,0,0] op_sel_hi:[1,1,1]
	v_pk_fma_f32 v[14:15], v[76:77], v[124:125], v[14:15] op_sel:[1,0,0] op_sel_hi:[1,1,1]
	v_pk_fma_f32 v[12:13], v[76:77], v[126:127], v[12:13] op_sel:[1,0,0] op_sel_hi:[1,1,1]
	v_pk_fma_f32 v[10:11], v[76:77], v[128:129], v[10:11] op_sel:[1,0,0] op_sel_hi:[1,1,1]
	v_pk_fma_f32 v[4:5], v[76:77], v[130:131], v[4:5] op_sel:[1,0,0] op_sel_hi:[1,1,1]
	global_load_dword v77, v[20:21], off
	v_lshl_add_u64 v[20:21], v[20:21], 0, s[4:5]
	ds_read_b128 v[116:119], v48 offset:960
	ds_read_b128 v[120:123], v48 offset:976
	ds_read_b128 v[124:127], v48 offset:992
	ds_read_b128 v[128:131], v48 offset:1008
	s_waitcnt lgkmcnt(4)
	s_waitcnt vmcnt(31)
	v_pk_fma_f32 v[24:25], v[78:79], v[100:101], v[24:25] op_sel_hi:[0,1,1]
	v_pk_fma_f32 v[22:23], v[78:79], v[102:103], v[22:23] op_sel_hi:[0,1,1]
	v_pk_fma_f32 v[18:19], v[78:79], v[104:105], v[18:19] op_sel_hi:[0,1,1]
	v_pk_fma_f32 v[16:17], v[78:79], v[106:107], v[16:17] op_sel_hi:[0,1,1]
	v_pk_fma_f32 v[14:15], v[78:79], v[108:109], v[14:15] op_sel_hi:[0,1,1]
	v_pk_fma_f32 v[12:13], v[78:79], v[110:111], v[12:13] op_sel_hi:[0,1,1]
	v_pk_fma_f32 v[10:11], v[78:79], v[112:113], v[10:11] op_sel_hi:[0,1,1]
	v_pk_fma_f32 v[4:5], v[78:79], v[114:115], v[4:5] op_sel_hi:[0,1,1]
	global_load_dword v78, v[20:21], off
	v_lshl_add_u64 v[20:21], v[20:21], 0, s[4:5]
	ds_read_b128 v[100:103], v48 offset:1024
	ds_read_b128 v[104:107], v48 offset:1040
	ds_read_b128 v[108:111], v48 offset:1056
	ds_read_b128 v[112:115], v48 offset:1072
	s_waitcnt lgkmcnt(4)
	s_waitcnt vmcnt(31)
	v_pk_fma_f32 v[24:25], v[78:79], v[116:117], v[24:25] op_sel:[1,0,0] op_sel_hi:[1,1,1]
	v_pk_fma_f32 v[22:23], v[78:79], v[118:119], v[22:23] op_sel:[1,0,0] op_sel_hi:[1,1,1]
	v_pk_fma_f32 v[18:19], v[78:79], v[120:121], v[18:19] op_sel:[1,0,0] op_sel_hi:[1,1,1]
	v_pk_fma_f32 v[16:17], v[78:79], v[122:123], v[16:17] op_sel:[1,0,0] op_sel_hi:[1,1,1]
	v_pk_fma_f32 v[14:15], v[78:79], v[124:125], v[14:15] op_sel:[1,0,0] op_sel_hi:[1,1,1]
	v_pk_fma_f32 v[12:13], v[78:79], v[126:127], v[12:13] op_sel:[1,0,0] op_sel_hi:[1,1,1]
	v_pk_fma_f32 v[10:11], v[78:79], v[128:129], v[10:11] op_sel:[1,0,0] op_sel_hi:[1,1,1]
	v_pk_fma_f32 v[4:5], v[78:79], v[130:131], v[4:5] op_sel:[1,0,0] op_sel_hi:[1,1,1]
	global_load_dword v79, v[20:21], off
	v_lshl_add_u64 v[20:21], v[20:21], 0, s[4:5]
	ds_read_b128 v[116:119], v48 offset:1088
	ds_read_b128 v[120:123], v48 offset:1104
	ds_read_b128 v[124:127], v48 offset:1120
	ds_read_b128 v[128:131], v48 offset:1136
	s_waitcnt lgkmcnt(4)
	s_waitcnt vmcnt(31)
	v_pk_fma_f32 v[24:25], v[80:81], v[100:101], v[24:25] op_sel_hi:[0,1,1]
	v_pk_fma_f32 v[22:23], v[80:81], v[102:103], v[22:23] op_sel_hi:[0,1,1]
	v_pk_fma_f32 v[18:19], v[80:81], v[104:105], v[18:19] op_sel_hi:[0,1,1]
	v_pk_fma_f32 v[16:17], v[80:81], v[106:107], v[16:17] op_sel_hi:[0,1,1]
	v_pk_fma_f32 v[14:15], v[80:81], v[108:109], v[14:15] op_sel_hi:[0,1,1]
	v_pk_fma_f32 v[12:13], v[80:81], v[110:111], v[12:13] op_sel_hi:[0,1,1]
	v_pk_fma_f32 v[10:11], v[80:81], v[112:113], v[10:11] op_sel_hi:[0,1,1]
	v_pk_fma_f32 v[4:5], v[80:81], v[114:115], v[4:5] op_sel_hi:[0,1,1]
	global_load_dword v80, v[20:21], off
	v_lshl_add_u64 v[20:21], v[20:21], 0, s[4:5]
	ds_read_b128 v[100:103], v48 offset:1152
	ds_read_b128 v[104:107], v48 offset:1168
	ds_read_b128 v[108:111], v48 offset:1184
	ds_read_b128 v[112:115], v48 offset:1200
	s_waitcnt lgkmcnt(4)
	s_waitcnt vmcnt(31)
	v_pk_fma_f32 v[24:25], v[80:81], v[116:117], v[24:25] op_sel:[1,0,0] op_sel_hi:[1,1,1]
	v_pk_fma_f32 v[22:23], v[80:81], v[118:119], v[22:23] op_sel:[1,0,0] op_sel_hi:[1,1,1]
	v_pk_fma_f32 v[18:19], v[80:81], v[120:121], v[18:19] op_sel:[1,0,0] op_sel_hi:[1,1,1]
	v_pk_fma_f32 v[16:17], v[80:81], v[122:123], v[16:17] op_sel:[1,0,0] op_sel_hi:[1,1,1]
	v_pk_fma_f32 v[14:15], v[80:81], v[124:125], v[14:15] op_sel:[1,0,0] op_sel_hi:[1,1,1]
	v_pk_fma_f32 v[12:13], v[80:81], v[126:127], v[12:13] op_sel:[1,0,0] op_sel_hi:[1,1,1]
	v_pk_fma_f32 v[10:11], v[80:81], v[128:129], v[10:11] op_sel:[1,0,0] op_sel_hi:[1,1,1]
	v_pk_fma_f32 v[4:5], v[80:81], v[130:131], v[4:5] op_sel:[1,0,0] op_sel_hi:[1,1,1]
	global_load_dword v81, v[20:21], off
	v_lshl_add_u64 v[20:21], v[20:21], 0, s[4:5]
	ds_read_b128 v[116:119], v48 offset:1216
	ds_read_b128 v[120:123], v48 offset:1232
	ds_read_b128 v[124:127], v48 offset:1248
	ds_read_b128 v[128:131], v48 offset:1264
	s_waitcnt lgkmcnt(4)
	s_waitcnt vmcnt(31)
; __device__ __forceinline__ void mod_item(const int tid, float* cs, const Params& p, int item) {
;     ...
; #pragma unroll 8
;     for (int k = 0; k < 256; ++k) {
;         const float wv = w[(size_t)k * 6144];
;         const f32x4 c0 = *(const f32x4*)(cs + k * 16), c1 = *(const f32x4*)(cs + k * 16 + 4), c2 = *(const f32x4*)(cs + k * 16 + 8), c3 = *(const f32x4*)(cs + k * 16 + 12);
; #pragma unroll
;         for (int j = 0; j < 4; ++j) { acc[j] += wv * c0[j]; acc[4 + j] += wv * c1[j]; acc[8 + j] += wv * c2[j]; acc[12 + j] += wv * c3[j]; }
;     }
	v_pk_fma_f32 v[24:25], v[82:83], v[100:101], v[24:25] op_sel_hi:[0,1,1]
	v_pk_fma_f32 v[22:23], v[82:83], v[102:103], v[22:23] op_sel_hi:[0,1,1]
	v_pk_fma_f32 v[18:19], v[82:83], v[104:105], v[18:19] op_sel_hi:[0,1,1]
	v_pk_fma_f32 v[16:17], v[82:83], v[106:107], v[16:17] op_sel_hi:[0,1,1]
	v_pk_fma_f32 v[14:15], v[82:83], v[108:109], v[14:15] op_sel_hi:[0,1,1]
	v_pk_fma_f32 v[12:13], v[82:83], v[110:111], v[12:13] op_sel_hi:[0,1,1]
	v_pk_fma_f32 v[10:11], v[82:83], v[112:113], v[10:11] op_sel_hi:[0,1,1]
	v_pk_fma_f32 v[4:5], v[82:83], v[114:115], v[4:5] op_sel_hi:[0,1,1]
	global_load_dword v82, v[20:21], off
	v_lshl_add_u64 v[20:21], v[20:21], 0, s[4:5]
	ds_read_b128 v[100:103], v48 offset:1280
	ds_read_b128 v[104:107], v48 offset:1296
	ds_read_b128 v[108:111], v48 offset:1312
	ds_read_b128 v[112:115], v48 offset:1328
	s_waitcnt lgkmcnt(4)
	s_waitcnt vmcnt(31)
	v_pk_fma_f32 v[24:25], v[82:83], v[116:117], v[24:25] op_sel:[1,0,0] op_sel_hi:[1,1,1]
	v_pk_fma_f32 v[22:23], v[82:83], v[118:119], v[22:23] op_sel:[1,0,0] op_sel_hi:[1,1,1]
	v_pk_fma_f32 v[18:19], v[82:83], v[120:121], v[18:19] op_sel:[1,0,0] op_sel_hi:[1,1,1]
	v_pk_fma_f32 v[16:17], v[82:83], v[122:123], v[16:17] op_sel:[1,0,0] op_sel_hi:[1,1,1]
	v_pk_fma_f32 v[14:15], v[82:83], v[124:125], v[14:15] op_sel:[1,0,0] op_sel_hi:[1,1,1]
	v_pk_fma_f32 v[12:13], v[82:83], v[126:127], v[12:13] op_sel:[1,0,0] op_sel_hi:[1,1,1]
	v_pk_fma_f32 v[10:11], v[82:83], v[128:129], v[10:11] op_sel:[1,0,0] op_sel_hi:[1,1,1]
	v_pk_fma_f32 v[4:5], v[82:83], v[130:131], v[4:5] op_sel:[1,0,0] op_sel_hi:[1,1,1]
	global_load_dword v83, v[20:21], off
	v_lshl_add_u64 v[20:21], v[20:21], 0, s[4:5]
	ds_read_b128 v[116:119], v48 offset:1344
	ds_read_b128 v[120:123], v48 offset:1360
	ds_read_b128 v[124:127], v48 offset:1376
	ds_read_b128 v[128:131], v48 offset:1392
	s_waitcnt lgkmcnt(4)
	s_waitcnt vmcnt(31)
	v_pk_fma_f32 v[24:25], v[84:85], v[100:101], v[24:25] op_sel_hi:[0,1,1]
	v_pk_fma_f32 v[22:23], v[84:85], v[102:103], v[22:23] op_sel_hi:[0,1,1]
	v_pk_fma_f32 v[18:19], v[84:85], v[104:105], v[18:19] op_sel_hi:[0,1,1]
	v_pk_fma_f32 v[16:17], v[84:85], v[106:107], v[16:17] op_sel_hi:[0,1,1]
	v_pk_fma_f32 v[14:15], v[84:85], v[108:109], v[14:15] op_sel_hi:[0,1,1]
	v_pk_fma_f32 v[12:13], v[84:85], v[110:111], v[12:13] op_sel_hi:[0,1,1]
	v_pk_fma_f32 v[10:11], v[84:85], v[112:113], v[10:11] op_sel_hi:[0,1,1]
	v_pk_fma_f32 v[4:5], v[84:85], v[114:115], v[4:5] op_sel_hi:[0,1,1]
	global_load_dword v84, v[20:21], off
	v_lshl_add_u64 v[20:21], v[20:21], 0, s[4:5]
	ds_read_b128 v[100:103], v48 offset:1408
	ds_read_b128 v[104:107], v48 offset:1424
	ds_read_b128 v[108:111], v48 offset:1440
	ds_read_b128 v[112:115], v48 offset:1456
	s_waitcnt lgkmcnt(4)
	s_waitcnt vmcnt(31)
	v_pk_fma_f32 v[24:25], v[84:85], v[116:117], v[24:25] op_sel:[1,0,0] op_sel_hi:[1,1,1]
	v_pk_fma_f32 v[22:23], v[84:85], v[118:119], v[22:23] op_sel:[1,0,0] op_sel_hi:[1,1,1]
	v_pk_fma_f32 v[18:19], v[84:85], v[120:121], v[18:19] op_sel:[1,0,0] op_sel_hi:[1,1,1]
	v_pk_fma_f32 v[16:17], v[84:85], v[122:123], v[16:17] op_sel:[1,0,0] op_sel_hi:[1,1,1]
	v_pk_fma_f32 v[14:15], v[84:85], v[124:125], v[14:15] op_sel:[1,0,0] op_sel_hi:[1,1,1]
	v_pk_fma_f32 v[12:13], v[84:85], v[126:127], v[12:13] op_sel:[1,0,0] op_sel_hi:[1,1,1]
	v_pk_fma_f32 v[10:11], v[84:85], v[128:129], v[10:11] op_sel:[1,0,0] op_sel_hi:[1,1,1]
	v_pk_fma_f32 v[4:5], v[84:85], v[130:131], v[4:5] op_sel:[1,0,0] op_sel_hi:[1,1,1]
	global_load_dword v85, v[20:21], off
	v_lshl_add_u64 v[20:21], v[20:21], 0, s[4:5]
	ds_read_b128 v[116:119], v48 offset:1472
	ds_read_b128 v[120:123], v48 offset:1488
	ds_read_b128 v[124:127], v48 offset:1504
	ds_read_b128 v[128:131], v48 offset:1520
	s_waitcnt lgkmcnt(4)
	s_waitcnt vmcnt(31)
	v_pk_fma_f32 v[24:25], v[86:87], v[100:101], v[24:25] op_sel_hi:[0,1,1]
	v_pk_fma_f32 v[22:23], v[86:87], v[102:103], v[22:23] op_sel_hi:[0,1,1]
	v_pk_fma_f32 v[18:19], v[86:87], v[104:105], v[18:19] op_sel_hi:[0,1,1]
	v_pk_fma_f32 v[16:17], v[86:87], v[106:107], v[16:17] op_sel_hi:[0,1,1]
	v_pk_fma_f32 v[14:15], v[86:87], v[108:109], v[14:15] op_sel_hi:[0,1,1]
	v_pk_fma_f32 v[12:13], v[86:87], v[110:111], v[12:13] op_sel_hi:[0,1,1]
	v_pk_fma_f32 v[10:11], v[86:87], v[112:113], v[10:11] op_sel_hi:[0,1,1]
	v_pk_fma_f32 v[4:5], v[86:87], v[114:115], v[4:5] op_sel_hi:[0,1,1]
	global_load_dword v86, v[20:21], off
	v_lshl_add_u64 v[20:21], v[20:21], 0, s[4:5]
	ds_read_b128 v[100:103], v48 offset:1536
	ds_read_b128 v[104:107], v48 offset:1552
	ds_read_b128 v[108:111], v48 offset:1568
	ds_read_b128 v[112:115], v48 offset:1584
	s_waitcnt lgkmcnt(4)
	s_waitcnt vmcnt(31)
	v_pk_fma_f32 v[24:25], v[86:87], v[116:117], v[24:25] op_sel:[1,0,0] op_sel_hi:[1,1,1]
	v_pk_fma_f32 v[22:23], v[86:87], v[118:119], v[22:23] op_sel:[1,0,0] op_sel_hi:[1,1,1]
	v_pk_fma_f32 v[18:19], v[86:87], v[120:121], v[18:19] op_sel:[1,0,0] op_sel_hi:[1,1,1]
	v_pk_fma_f32 v[16:17], v[86:87], v[122:123], v[16:17] op_sel:[1,0,0] op_sel_hi:[1,1,1]
	v_pk_fma_f32 v[14:15], v[86:87], v[124:125], v[14:15] op_sel:[1,0,0] op_sel_hi:[1,1,1]
	v_pk_fma_f32 v[12:13], v[86:87], v[126:127], v[12:13] op_sel:[1,0,0] op_sel_hi:[1,1,1]
	v_pk_fma_f32 v[10:11], v[86:87], v[128:129], v[10:11] op_sel:[1,0,0] op_sel_hi:[1,1,1]
	v_pk_fma_f32 v[4:5], v[86:87], v[130:131], v[4:5] op_sel:[1,0,0] op_sel_hi:[1,1,1]
	global_load_dword v87, v[20:21], off
	v_lshl_add_u64 v[20:21], v[20:21], 0, s[4:5]
	ds_read_b128 v[116:119], v48 offset:1600
	ds_read_b128 v[120:123], v48 offset:1616
	ds_read_b128 v[124:127], v48 offset:1632
	ds_read_b128 v[128:131], v48 offset:1648
	s_waitcnt lgkmcnt(4)
	s_waitcnt vmcnt(31)
; __device__ __forceinline__ void mod_item(const int tid, float* cs, const Params& p, int item) {
;     ...
; #pragma unroll 8
;     for (int k = 0; k < 256; ++k) {
;         const float wv = w[(size_t)k * 6144];
;         const f32x4 c0 = *(const f32x4*)(cs + k * 16), c1 = *(const f32x4*)(cs + k * 16 + 4), c2 = *(const f32x4*)(cs + k * 16 + 8), c3 = *(const f32x4*)(cs + k * 16 + 12);
; #pragma unroll
;         for (int j = 0; j < 4; ++j) { acc[j] += wv * c0[j]; acc[4 + j] += wv * c1[j]; acc[8 + j] += wv * c2[j]; acc[12 + j] += wv * c3[j]; }
;     }
	v_pk_fma_f32 v[24:25], v[88:89], v[100:101], v[24:25] op_sel_hi:[0,1,1]
	v_pk_fma_f32 v[22:23], v[88:89], v[102:103], v[22:23] op_sel_hi:[0,1,1]
	v_pk_fma_f32 v[18:19], v[88:89], v[104:105], v[18:19] op_sel_hi:[0,1,1]
	v_pk_fma_f32 v[16:17], v[88:89], v[106:107], v[16:17] op_sel_hi:[0,1,1]
	v_pk_fma_f32 v[14:15], v[88:89], v[108:109], v[14:15] op_sel_hi:[0,1,1]
	v_pk_fma_f32 v[12:13], v[88:89], v[110:111], v[12:13] op_sel_hi:[0,1,1]
	v_pk_fma_f32 v[10:11], v[88:89], v[112:113], v[10:11] op_sel_hi:[0,1,1]
	v_pk_fma_f32 v[4:5], v[88:89], v[114:115], v[4:5] op_sel_hi:[0,1,1]
	global_load_dword v88, v[20:21], off
	v_lshl_add_u64 v[20:21], v[20:21], 0, s[4:5]
	ds_read_b128 v[100:103], v48 offset:1664
	ds_read_b128 v[104:107], v48 offset:1680
	ds_read_b128 v[108:111], v48 offset:1696
	ds_read_b128 v[112:115], v48 offset:1712
	s_waitcnt lgkmcnt(4)
	s_waitcnt vmcnt(31)
	v_pk_fma_f32 v[24:25], v[88:89], v[116:117], v[24:25] op_sel:[1,0,0] op_sel_hi:[1,1,1]
	v_pk_fma_f32 v[22:23], v[88:89], v[118:119], v[22:23] op_sel:[1,0,0] op_sel_hi:[1,1,1]
	v_pk_fma_f32 v[18:19], v[88:89], v[120:121], v[18:19] op_sel:[1,0,0] op_sel_hi:[1,1,1]
	v_pk_fma_f32 v[16:17], v[88:89], v[122:123], v[16:17] op_sel:[1,0,0] op_sel_hi:[1,1,1]
	v_pk_fma_f32 v[14:15], v[88:89], v[124:125], v[14:15] op_sel:[1,0,0] op_sel_hi:[1,1,1]
	v_pk_fma_f32 v[12:13], v[88:89], v[126:127], v[12:13] op_sel:[1,0,0] op_sel_hi:[1,1,1]
	v_pk_fma_f32 v[10:11], v[88:89], v[128:129], v[10:11] op_sel:[1,0,0] op_sel_hi:[1,1,1]
	v_pk_fma_f32 v[4:5], v[88:89], v[130:131], v[4:5] op_sel:[1,0,0] op_sel_hi:[1,1,1]
	global_load_dword v89, v[20:21], off
	v_lshl_add_u64 v[20:21], v[20:21], 0, s[4:5]
	ds_read_b128 v[116:119], v48 offset:1728
	ds_read_b128 v[120:123], v48 offset:1744
	ds_read_b128 v[124:127], v48 offset:1760
	ds_read_b128 v[128:131], v48 offset:1776
	s_waitcnt lgkmcnt(4)
	s_waitcnt vmcnt(31)
	v_pk_fma_f32 v[24:25], v[90:91], v[100:101], v[24:25] op_sel_hi:[0,1,1]
	v_pk_fma_f32 v[22:23], v[90:91], v[102:103], v[22:23] op_sel_hi:[0,1,1]
	v_pk_fma_f32 v[18:19], v[90:91], v[104:105], v[18:19] op_sel_hi:[0,1,1]
	v_pk_fma_f32 v[16:17], v[90:91], v[106:107], v[16:17] op_sel_hi:[0,1,1]
	v_pk_fma_f32 v[14:15], v[90:91], v[108:109], v[14:15] op_sel_hi:[0,1,1]
	v_pk_fma_f32 v[12:13], v[90:91], v[110:111], v[12:13] op_sel_hi:[0,1,1]
	v_pk_fma_f32 v[10:11], v[90:91], v[112:113], v[10:11] op_sel_hi:[0,1,1]
	v_pk_fma_f32 v[4:5], v[90:91], v[114:115], v[4:5] op_sel_hi:[0,1,1]
	global_load_dword v90, v[20:21], off
	v_lshl_add_u64 v[20:21], v[20:21], 0, s[4:5]
	ds_read_b128 v[100:103], v48 offset:1792
	ds_read_b128 v[104:107], v48 offset:1808
	ds_read_b128 v[108:111], v48 offset:1824
	ds_read_b128 v[112:115], v48 offset:1840
	s_waitcnt lgkmcnt(4)
	s_waitcnt vmcnt(31)
	v_pk_fma_f32 v[24:25], v[90:91], v[116:117], v[24:25] op_sel:[1,0,0] op_sel_hi:[1,1,1]
	v_pk_fma_f32 v[22:23], v[90:91], v[118:119], v[22:23] op_sel:[1,0,0] op_sel_hi:[1,1,1]
	v_pk_fma_f32 v[18:19], v[90:91], v[120:121], v[18:19] op_sel:[1,0,0] op_sel_hi:[1,1,1]
	v_pk_fma_f32 v[16:17], v[90:91], v[122:123], v[16:17] op_sel:[1,0,0] op_sel_hi:[1,1,1]
	v_pk_fma_f32 v[14:15], v[90:91], v[124:125], v[14:15] op_sel:[1,0,0] op_sel_hi:[1,1,1]
	v_pk_fma_f32 v[12:13], v[90:91], v[126:127], v[12:13] op_sel:[1,0,0] op_sel_hi:[1,1,1]
	v_pk_fma_f32 v[10:11], v[90:91], v[128:129], v[10:11] op_sel:[1,0,0] op_sel_hi:[1,1,1]
	v_pk_fma_f32 v[4:5], v[90:91], v[130:131], v[4:5] op_sel:[1,0,0] op_sel_hi:[1,1,1]
	global_load_dword v91, v[20:21], off
	v_lshl_add_u64 v[20:21], v[20:21], 0, s[4:5]
	ds_read_b128 v[116:119], v48 offset:1856
	ds_read_b128 v[120:123], v48 offset:1872
	ds_read_b128 v[124:127], v48 offset:1888
	ds_read_b128 v[128:131], v48 offset:1904
	s_waitcnt lgkmcnt(4)
	s_waitcnt vmcnt(31)
	v_pk_fma_f32 v[24:25], v[92:93], v[100:101], v[24:25] op_sel_hi:[0,1,1]
	v_pk_fma_f32 v[22:23], v[92:93], v[102:103], v[22:23] op_sel_hi:[0,1,1]
	v_pk_fma_f32 v[18:19], v[92:93], v[104:105], v[18:19] op_sel_hi:[0,1,1]
	v_pk_fma_f32 v[16:17], v[92:93], v[106:107], v[16:17] op_sel_hi:[0,1,1]
	v_pk_fma_f32 v[14:15], v[92:93], v[108:109], v[14:15] op_sel_hi:[0,1,1]
	v_pk_fma_f32 v[12:13], v[92:93], v[110:111], v[12:13] op_sel_hi:[0,1,1]
	v_pk_fma_f32 v[10:11], v[92:93], v[112:113], v[10:11] op_sel_hi:[0,1,1]
	v_pk_fma_f32 v[4:5], v[92:93], v[114:115], v[4:5] op_sel_hi:[0,1,1]
	global_load_dword v92, v[20:21], off
	v_lshl_add_u64 v[20:21], v[20:21], 0, s[4:5]
	ds_read_b128 v[100:103], v48 offset:1920
	ds_read_b128 v[104:107], v48 offset:1936
	ds_read_b128 v[108:111], v48 offset:1952
	ds_read_b128 v[112:115], v48 offset:1968
	s_waitcnt lgkmcnt(4)
	s_waitcnt vmcnt(31)
	v_pk_fma_f32 v[24:25], v[92:93], v[116:117], v[24:25] op_sel:[1,0,0] op_sel_hi:[1,1,1]
	v_pk_fma_f32 v[22:23], v[92:93], v[118:119], v[22:23] op_sel:[1,0,0] op_sel_hi:[1,1,1]
	v_pk_fma_f32 v[18:19], v[92:93], v[120:121], v[18:19] op_sel:[1,0,0] op_sel_hi:[1,1,1]
	v_pk_fma_f32 v[16:17], v[92:93], v[122:123], v[16:17] op_sel:[1,0,0] op_sel_hi:[1,1,1]
	v_pk_fma_f32 v[14:15], v[92:93], v[124:125], v[14:15] op_sel:[1,0,0] op_sel_hi:[1,1,1]
	v_pk_fma_f32 v[12:13], v[92:93], v[126:127], v[12:13] op_sel:[1,0,0] op_sel_hi:[1,1,1]
	v_pk_fma_f32 v[10:11], v[92:93], v[128:129], v[10:11] op_sel:[1,0,0] op_sel_hi:[1,1,1]
	v_pk_fma_f32 v[4:5], v[92:93], v[130:131], v[4:5] op_sel:[1,0,0] op_sel_hi:[1,1,1]
	global_load_dword v93, v[20:21], off
	v_lshl_add_u64 v[20:21], v[20:21], 0, s[4:5]
	ds_read_b128 v[116:119], v48 offset:1984
	ds_read_b128 v[120:123], v48 offset:2000
	ds_read_b128 v[124:127], v48 offset:2016
	ds_read_b128 v[128:131], v48 offset:2032
	s_waitcnt lgkmcnt(4)
	s_waitcnt vmcnt(31)
; __device__ __forceinline__ void mod_item(const int tid, float* cs, const Params& p, int item) {
;     ...
; #pragma unroll 8
;     for (int k = 0; k < 256; ++k) {
;         const float wv = w[(size_t)k * 6144];
;         const f32x4 c0 = *(const f32x4*)(cs + k * 16), c1 = *(const f32x4*)(cs + k * 16 + 4), c2 = *(const f32x4*)(cs + k * 16 + 8), c3 = *(const f32x4*)(cs + k * 16 + 12);
; #pragma unroll
;         for (int j = 0; j < 4; ++j) { acc[j] += wv * c0[j]; acc[4 + j] += wv * c1[j]; acc[8 + j] += wv * c2[j]; acc[12 + j] += wv * c3[j]; }
;     }
	v_pk_fma_f32 v[24:25], v[94:95], v[100:101], v[24:25] op_sel_hi:[0,1,1]
	v_pk_fma_f32 v[22:23], v[94:95], v[102:103], v[22:23] op_sel_hi:[0,1,1]
	v_pk_fma_f32 v[18:19], v[94:95], v[104:105], v[18:19] op_sel_hi:[0,1,1]
	v_pk_fma_f32 v[16:17], v[94:95], v[106:107], v[16:17] op_sel_hi:[0,1,1]
	v_pk_fma_f32 v[14:15], v[94:95], v[108:109], v[14:15] op_sel_hi:[0,1,1]
	v_pk_fma_f32 v[12:13], v[94:95], v[110:111], v[12:13] op_sel_hi:[0,1,1]
	v_pk_fma_f32 v[10:11], v[94:95], v[112:113], v[10:11] op_sel_hi:[0,1,1]
	v_pk_fma_f32 v[4:5], v[94:95], v[114:115], v[4:5] op_sel_hi:[0,1,1]
	global_load_dword v94, v[20:21], off
	v_lshl_add_u64 v[20:21], v[20:21], 0, s[4:5]
	ds_read_b128 v[100:103], v48 offset:2048
	ds_read_b128 v[104:107], v48 offset:2064
	ds_read_b128 v[108:111], v48 offset:2080
	ds_read_b128 v[112:115], v48 offset:2096
	s_waitcnt lgkmcnt(4)
	s_waitcnt vmcnt(31)
	v_pk_fma_f32 v[24:25], v[94:95], v[116:117], v[24:25] op_sel:[1,0,0] op_sel_hi:[1,1,1]
	v_pk_fma_f32 v[22:23], v[94:95], v[118:119], v[22:23] op_sel:[1,0,0] op_sel_hi:[1,1,1]
	v_pk_fma_f32 v[18:19], v[94:95], v[120:121], v[18:19] op_sel:[1,0,0] op_sel_hi:[1,1,1]
	v_pk_fma_f32 v[16:17], v[94:95], v[122:123], v[16:17] op_sel:[1,0,0] op_sel_hi:[1,1,1]
	v_pk_fma_f32 v[14:15], v[94:95], v[124:125], v[14:15] op_sel:[1,0,0] op_sel_hi:[1,1,1]
	v_pk_fma_f32 v[12:13], v[94:95], v[126:127], v[12:13] op_sel:[1,0,0] op_sel_hi:[1,1,1]
	v_pk_fma_f32 v[10:11], v[94:95], v[128:129], v[10:11] op_sel:[1,0,0] op_sel_hi:[1,1,1]
	v_pk_fma_f32 v[4:5], v[94:95], v[130:131], v[4:5] op_sel:[1,0,0] op_sel_hi:[1,1,1]
	global_load_dword v95, v[20:21], off
	v_lshl_add_u64 v[20:21], v[20:21], 0, s[4:5]
	v_add_u32_e32 v48, 0x800, v48
	s_add_i32 s21, s21, -1
	s_cmp_lg_u32 s21, 0
	s_cbranch_scc1 .Lmod_loop
	ds_read_b128 v[116:119], v48 offset:64
	ds_read_b128 v[120:123], v48 offset:80
	ds_read_b128 v[124:127], v48 offset:96
	ds_read_b128 v[128:131], v48 offset:112
	s_waitcnt lgkmcnt(4)
	s_waitcnt vmcnt(31)
	v_pk_fma_f32 v[24:25], v[64:65], v[100:101], v[24:25] op_sel_hi:[0,1,1]
	v_pk_fma_f32 v[22:23], v[64:65], v[102:103], v[22:23] op_sel_hi:[0,1,1]
	v_pk_fma_f32 v[18:19], v[64:65], v[104:105], v[18:19] op_sel_hi:[0,1,1]
	v_pk_fma_f32 v[16:17], v[64:65], v[106:107], v[16:17] op_sel_hi:[0,1,1]
	v_pk_fma_f32 v[14:15], v[64:65], v[108:109], v[14:15] op_sel_hi:[0,1,1]
	v_pk_fma_f32 v[12:13], v[64:65], v[110:111], v[12:13] op_sel_hi:[0,1,1]
	v_pk_fma_f32 v[10:11], v[64:65], v[112:113], v[10:11] op_sel_hi:[0,1,1]
	v_pk_fma_f32 v[4:5], v[64:65], v[114:115], v[4:5] op_sel_hi:[0,1,1]
	ds_read_b128 v[100:103], v48 offset:128
	ds_read_b128 v[104:107], v48 offset:144
	ds_read_b128 v[108:111], v48 offset:160
	ds_read_b128 v[112:115], v48 offset:176
	s_waitcnt lgkmcnt(4)
	s_waitcnt vmcnt(30)
	v_pk_fma_f32 v[24:25], v[64:65], v[116:117], v[24:25] op_sel:[1,0,0] op_sel_hi:[1,1,1]
	v_pk_fma_f32 v[22:23], v[64:65], v[118:119], v[22:23] op_sel:[1,0,0] op_sel_hi:[1,1,1]
	v_pk_fma_f32 v[18:19], v[64:65], v[120:121], v[18:19] op_sel:[1,0,0] op_sel_hi:[1,1,1]
	v_pk_fma_f32 v[16:17], v[64:65], v[122:123], v[16:17] op_sel:[1,0,0] op_sel_hi:[1,1,1]
	v_pk_fma_f32 v[14:15], v[64:65], v[124:125], v[14:15] op_sel:[1,0,0] op_sel_hi:[1,1,1]
	v_pk_fma_f32 v[12:13], v[64:65], v[126:127], v[12:13] op_sel:[1,0,0] op_sel_hi:[1,1,1]
	v_pk_fma_f32 v[10:11], v[64:65], v[128:129], v[10:11] op_sel:[1,0,0] op_sel_hi:[1,1,1]
	v_pk_fma_f32 v[4:5], v[64:65], v[130:131], v[4:5] op_sel:[1,0,0] op_sel_hi:[1,1,1]
	ds_read_b128 v[116:119], v48 offset:192
	ds_read_b128 v[120:123], v48 offset:208
	ds_read_b128 v[124:127], v48 offset:224
	ds_read_b128 v[128:131], v48 offset:240
	s_waitcnt lgkmcnt(4)
	s_waitcnt vmcnt(29)
	v_pk_fma_f32 v[24:25], v[66:67], v[100:101], v[24:25] op_sel_hi:[0,1,1]
	v_pk_fma_f32 v[22:23], v[66:67], v[102:103], v[22:23] op_sel_hi:[0,1,1]
	v_pk_fma_f32 v[18:19], v[66:67], v[104:105], v[18:19] op_sel_hi:[0,1,1]
	v_pk_fma_f32 v[16:17], v[66:67], v[106:107], v[16:17] op_sel_hi:[0,1,1]
	v_pk_fma_f32 v[14:15], v[66:67], v[108:109], v[14:15] op_sel_hi:[0,1,1]
	v_pk_fma_f32 v[12:13], v[66:67], v[110:111], v[12:13] op_sel_hi:[0,1,1]
	v_pk_fma_f32 v[10:11], v[66:67], v[112:113], v[10:11] op_sel_hi:[0,1,1]
	v_pk_fma_f32 v[4:5], v[66:67], v[114:115], v[4:5] op_sel_hi:[0,1,1]
	ds_read_b128 v[100:103], v48 offset:256
	ds_read_b128 v[104:107], v48 offset:272
	ds_read_b128 v[108:111], v48 offset:288
	ds_read_b128 v[112:115], v48 offset:304
	s_waitcnt lgkmcnt(4)
	s_waitcnt vmcnt(28)
	v_pk_fma_f32 v[24:25], v[66:67], v[116:117], v[24:25] op_sel:[1,0,0] op_sel_hi:[1,1,1]
	v_pk_fma_f32 v[22:23], v[66:67], v[118:119], v[22:23] op_sel:[1,0,0] op_sel_hi:[1,1,1]
	v_pk_fma_f32 v[18:19], v[66:67], v[120:121], v[18:19] op_sel:[1,0,0] op_sel_hi:[1,1,1]
	v_pk_fma_f32 v[16:17], v[66:67], v[122:123], v[16:17] op_sel:[1,0,0] op_sel_hi:[1,1,1]
	v_pk_fma_f32 v[14:15], v[66:67], v[124:125], v[14:15] op_sel:[1,0,0] op_sel_hi:[1,1,1]
	v_pk_fma_f32 v[12:13], v[66:67], v[126:127], v[12:13] op_sel:[1,0,0] op_sel_hi:[1,1,1]
	v_pk_fma_f32 v[10:11], v[66:67], v[128:129], v[10:11] op_sel:[1,0,0] op_sel_hi:[1,1,1]
	v_pk_fma_f32 v[4:5], v[66:67], v[130:131], v[4:5] op_sel:[1,0,0] op_sel_hi:[1,1,1]
	ds_read_b128 v[116:119], v48 offset:320
	ds_read_b128 v[120:123], v48 offset:336
	ds_read_b128 v[124:127], v48 offset:352
	ds_read_b128 v[128:131], v48 offset:368
	s_waitcnt lgkmcnt(4)
	s_waitcnt vmcnt(27)
; __device__ __forceinline__ void mod_item(const int tid, float* cs, const Params& p, int item) {
;     ...
; #pragma unroll 8
;     for (int k = 0; k < 256; ++k) {
;         const float wv = w[(size_t)k * 6144];
;         const f32x4 c0 = *(const f32x4*)(cs + k * 16), c1 = *(const f32x4*)(cs + k * 16 + 4), c2 = *(const f32x4*)(cs + k * 16 + 8), c3 = *(const f32x4*)(cs + k * 16 + 12);
; #pragma unroll
;         for (int j = 0; j < 4; ++j) { acc[j] += wv * c0[j]; acc[4 + j] += wv * c1[j]; acc[8 + j] += wv * c2[j]; acc[12 + j] += wv * c3[j]; }
;     }
	v_pk_fma_f32 v[24:25], v[68:69], v[100:101], v[24:25] op_sel_hi:[0,1,1]
	v_pk_fma_f32 v[22:23], v[68:69], v[102:103], v[22:23] op_sel_hi:[0,1,1]
	v_pk_fma_f32 v[18:19], v[68:69], v[104:105], v[18:19] op_sel_hi:[0,1,1]
	v_pk_fma_f32 v[16:17], v[68:69], v[106:107], v[16:17] op_sel_hi:[0,1,1]
	v_pk_fma_f32 v[14:15], v[68:69], v[108:109], v[14:15] op_sel_hi:[0,1,1]
	v_pk_fma_f32 v[12:13], v[68:69], v[110:111], v[12:13] op_sel_hi:[0,1,1]
	v_pk_fma_f32 v[10:11], v[68:69], v[112:113], v[10:11] op_sel_hi:[0,1,1]
	v_pk_fma_f32 v[4:5], v[68:69], v[114:115], v[4:5] op_sel_hi:[0,1,1]
	ds_read_b128 v[100:103], v48 offset:384
	ds_read_b128 v[104:107], v48 offset:400
	ds_read_b128 v[108:111], v48 offset:416
	ds_read_b128 v[112:115], v48 offset:432
	s_waitcnt lgkmcnt(4)
	s_waitcnt vmcnt(26)
	v_pk_fma_f32 v[24:25], v[68:69], v[116:117], v[24:25] op_sel:[1,0,0] op_sel_hi:[1,1,1]
	v_pk_fma_f32 v[22:23], v[68:69], v[118:119], v[22:23] op_sel:[1,0,0] op_sel_hi:[1,1,1]
	v_pk_fma_f32 v[18:19], v[68:69], v[120:121], v[18:19] op_sel:[1,0,0] op_sel_hi:[1,1,1]
	v_pk_fma_f32 v[16:17], v[68:69], v[122:123], v[16:17] op_sel:[1,0,0] op_sel_hi:[1,1,1]
	v_pk_fma_f32 v[14:15], v[68:69], v[124:125], v[14:15] op_sel:[1,0,0] op_sel_hi:[1,1,1]
	v_pk_fma_f32 v[12:13], v[68:69], v[126:127], v[12:13] op_sel:[1,0,0] op_sel_hi:[1,1,1]
	v_pk_fma_f32 v[10:11], v[68:69], v[128:129], v[10:11] op_sel:[1,0,0] op_sel_hi:[1,1,1]
	v_pk_fma_f32 v[4:5], v[68:69], v[130:131], v[4:5] op_sel:[1,0,0] op_sel_hi:[1,1,1]
	ds_read_b128 v[116:119], v48 offset:448
	ds_read_b128 v[120:123], v48 offset:464
	ds_read_b128 v[124:127], v48 offset:480
	ds_read_b128 v[128:131], v48 offset:496
	s_waitcnt lgkmcnt(4)
	s_waitcnt vmcnt(25)
	v_pk_fma_f32 v[24:25], v[70:71], v[100:101], v[24:25] op_sel_hi:[0,1,1]
	v_pk_fma_f32 v[22:23], v[70:71], v[102:103], v[22:23] op_sel_hi:[0,1,1]
	v_pk_fma_f32 v[18:19], v[70:71], v[104:105], v[18:19] op_sel_hi:[0,1,1]
	v_pk_fma_f32 v[16:17], v[70:71], v[106:107], v[16:17] op_sel_hi:[0,1,1]
	v_pk_fma_f32 v[14:15], v[70:71], v[108:109], v[14:15] op_sel_hi:[0,1,1]
	v_pk_fma_f32 v[12:13], v[70:71], v[110:111], v[12:13] op_sel_hi:[0,1,1]
	v_pk_fma_f32 v[10:11], v[70:71], v[112:113], v[10:11] op_sel_hi:[0,1,1]
	v_pk_fma_f32 v[4:5], v[70:71], v[114:115], v[4:5] op_sel_hi:[0,1,1]
	ds_read_b128 v[100:103], v48 offset:512
	ds_read_b128 v[104:107], v48 offset:528
	ds_read_b128 v[108:111], v48 offset:544
	ds_read_b128 v[112:115], v48 offset:560
	s_waitcnt lgkmcnt(4)
	s_waitcnt vmcnt(24)
	v_pk_fma_f32 v[24:25], v[70:71], v[116:117], v[24:25] op_sel:[1,0,0] op_sel_hi:[1,1,1]
	v_pk_fma_f32 v[22:23], v[70:71], v[118:119], v[22:23] op_sel:[1,0,0] op_sel_hi:[1,1,1]
	v_pk_fma_f32 v[18:19], v[70:71], v[120:121], v[18:19] op_sel:[1,0,0] op_sel_hi:[1,1,1]
	v_pk_fma_f32 v[16:17], v[70:71], v[122:123], v[16:17] op_sel:[1,0,0] op_sel_hi:[1,1,1]
	v_pk_fma_f32 v[14:15], v[70:71], v[124:125], v[14:15] op_sel:[1,0,0] op_sel_hi:[1,1,1]
	v_pk_fma_f32 v[12:13], v[70:71], v[126:127], v[12:13] op_sel:[1,0,0] op_sel_hi:[1,1,1]
	v_pk_fma_f32 v[10:11], v[70:71], v[128:129], v[10:11] op_sel:[1,0,0] op_sel_hi:[1,1,1]
	v_pk_fma_f32 v[4:5], v[70:71], v[130:131], v[4:5] op_sel:[1,0,0] op_sel_hi:[1,1,1]
	ds_read_b128 v[116:119], v48 offset:576
	ds_read_b128 v[120:123], v48 offset:592
	ds_read_b128 v[124:127], v48 offset:608
	ds_read_b128 v[128:131], v48 offset:624
	s_waitcnt lgkmcnt(4)
	s_waitcnt vmcnt(23)
	v_pk_fma_f32 v[24:25], v[72:73], v[100:101], v[24:25] op_sel_hi:[0,1,1]
	v_pk_fma_f32 v[22:23], v[72:73], v[102:103], v[22:23] op_sel_hi:[0,1,1]
	v_pk_fma_f32 v[18:19], v[72:73], v[104:105], v[18:19] op_sel_hi:[0,1,1]
	v_pk_fma_f32 v[16:17], v[72:73], v[106:107], v[16:17] op_sel_hi:[0,1,1]
	v_pk_fma_f32 v[14:15], v[72:73], v[108:109], v[14:15] op_sel_hi:[0,1,1]
	v_pk_fma_f32 v[12:13], v[72:73], v[110:111], v[12:13] op_sel_hi:[0,1,1]
	v_pk_fma_f32 v[10:11], v[72:73], v[112:113], v[10:11] op_sel_hi:[0,1,1]
	v_pk_fma_f32 v[4:5], v[72:73], v[114:115], v[4:5] op_sel_hi:[0,1,1]
	ds_read_b128 v[100:103], v48 offset:640
	ds_read_b128 v[104:107], v48 offset:656
	ds_read_b128 v[108:111], v48 offset:672
	ds_read_b128 v[112:115], v48 offset:688
	s_waitcnt lgkmcnt(4)
	s_waitcnt vmcnt(22)
	v_pk_fma_f32 v[24:25], v[72:73], v[116:117], v[24:25] op_sel:[1,0,0] op_sel_hi:[1,1,1]
	v_pk_fma_f32 v[22:23], v[72:73], v[118:119], v[22:23] op_sel:[1,0,0] op_sel_hi:[1,1,1]
	v_pk_fma_f32 v[18:19], v[72:73], v[120:121], v[18:19] op_sel:[1,0,0] op_sel_hi:[1,1,1]
	v_pk_fma_f32 v[16:17], v[72:73], v[122:123], v[16:17] op_sel:[1,0,0] op_sel_hi:[1,1,1]
	v_pk_fma_f32 v[14:15], v[72:73], v[124:125], v[14:15] op_sel:[1,0,0] op_sel_hi:[1,1,1]
	v_pk_fma_f32 v[12:13], v[72:73], v[126:127], v[12:13] op_sel:[1,0,0] op_sel_hi:[1,1,1]
	v_pk_fma_f32 v[10:11], v[72:73], v[128:129], v[10:11] op_sel:[1,0,0] op_sel_hi:[1,1,1]
	v_pk_fma_f32 v[4:5], v[72:73], v[130:131], v[4:5] op_sel:[1,0,0] op_sel_hi:[1,1,1]
	ds_read_b128 v[116:119], v48 offset:704
	ds_read_b128 v[120:123], v48 offset:720
	ds_read_b128 v[124:127], v48 offset:736
	ds_read_b128 v[128:131], v48 offset:752
	s_waitcnt lgkmcnt(4)
	s_waitcnt vmcnt(21)
	v_pk_fma_f32 v[24:25], v[74:75], v[100:101], v[24:25] op_sel_hi:[0,1,1]
	v_pk_fma_f32 v[22:23], v[74:75], v[102:103], v[22:23] op_sel_hi:[0,1,1]
	v_pk_fma_f32 v[18:19], v[74:75], v[104:105], v[18:19] op_sel_hi:[0,1,1]
	v_pk_fma_f32 v[16:17], v[74:75], v[106:107], v[16:17] op_sel_hi:[0,1,1]
	v_pk_fma_f32 v[14:15], v[74:75], v[108:109], v[14:15] op_sel_hi:[0,1,1]
	v_pk_fma_f32 v[12:13], v[74:75], v[110:111], v[12:13] op_sel_hi:[0,1,1]
	v_pk_fma_f32 v[10:11], v[74:75], v[112:113], v[10:11] op_sel_hi:[0,1,1]
	v_pk_fma_f32 v[4:5], v[74:75], v[114:115], v[4:5] op_sel_hi:[0,1,1]
	ds_read_b128 v[100:103], v48 offset:768
	ds_read_b128 v[104:107], v48 offset:784
	ds_read_b128 v[108:111], v48 offset:800
	ds_read_b128 v[112:115], v48 offset:816
	s_waitcnt lgkmcnt(4)
; __device__ __forceinline__ void mod_item(const int tid, float* cs, const Params& p, int item) {
;     ...
; #pragma unroll 8
;     for (int k = 0; k < 256; ++k) {
;         const float wv = w[(size_t)k * 6144];
;         const f32x4 c0 = *(const f32x4*)(cs + k * 16), c1 = *(const f32x4*)(cs + k * 16 + 4), c2 = *(const f32x4*)(cs + k * 16 + 8), c3 = *(const f32x4*)(cs + k * 16 + 12);
; #pragma unroll
;         for (int j = 0; j < 4; ++j) { acc[j] += wv * c0[j]; acc[4 + j] += wv * c1[j]; acc[8 + j] += wv * c2[j]; acc[12 + j] += wv * c3[j]; }
;     }
	s_waitcnt vmcnt(20)
	v_pk_fma_f32 v[24:25], v[74:75], v[116:117], v[24:25] op_sel:[1,0,0] op_sel_hi:[1,1,1]
	v_pk_fma_f32 v[22:23], v[74:75], v[118:119], v[22:23] op_sel:[1,0,0] op_sel_hi:[1,1,1]
	v_pk_fma_f32 v[18:19], v[74:75], v[120:121], v[18:19] op_sel:[1,0,0] op_sel_hi:[1,1,1]
	v_pk_fma_f32 v[16:17], v[74:75], v[122:123], v[16:17] op_sel:[1,0,0] op_sel_hi:[1,1,1]
	v_pk_fma_f32 v[14:15], v[74:75], v[124:125], v[14:15] op_sel:[1,0,0] op_sel_hi:[1,1,1]
	v_pk_fma_f32 v[12:13], v[74:75], v[126:127], v[12:13] op_sel:[1,0,0] op_sel_hi:[1,1,1]
	v_pk_fma_f32 v[10:11], v[74:75], v[128:129], v[10:11] op_sel:[1,0,0] op_sel_hi:[1,1,1]
	v_pk_fma_f32 v[4:5], v[74:75], v[130:131], v[4:5] op_sel:[1,0,0] op_sel_hi:[1,1,1]
	ds_read_b128 v[116:119], v48 offset:832
	ds_read_b128 v[120:123], v48 offset:848
	ds_read_b128 v[124:127], v48 offset:864
	ds_read_b128 v[128:131], v48 offset:880
	s_waitcnt lgkmcnt(4)
	s_waitcnt vmcnt(19)
	v_pk_fma_f32 v[24:25], v[76:77], v[100:101], v[24:25] op_sel_hi:[0,1,1]
	v_pk_fma_f32 v[22:23], v[76:77], v[102:103], v[22:23] op_sel_hi:[0,1,1]
	v_pk_fma_f32 v[18:19], v[76:77], v[104:105], v[18:19] op_sel_hi:[0,1,1]
	v_pk_fma_f32 v[16:17], v[76:77], v[106:107], v[16:17] op_sel_hi:[0,1,1]
	v_pk_fma_f32 v[14:15], v[76:77], v[108:109], v[14:15] op_sel_hi:[0,1,1]
	v_pk_fma_f32 v[12:13], v[76:77], v[110:111], v[12:13] op_sel_hi:[0,1,1]
	v_pk_fma_f32 v[10:11], v[76:77], v[112:113], v[10:11] op_sel_hi:[0,1,1]
	v_pk_fma_f32 v[4:5], v[76:77], v[114:115], v[4:5] op_sel_hi:[0,1,1]
	ds_read_b128 v[100:103], v48 offset:896
	ds_read_b128 v[104:107], v48 offset:912
	ds_read_b128 v[108:111], v48 offset:928
	ds_read_b128 v[112:115], v48 offset:944
	s_waitcnt lgkmcnt(4)
	s_waitcnt vmcnt(18)
	v_pk_fma_f32 v[24:25], v[76:77], v[116:117], v[24:25] op_sel:[1,0,0] op_sel_hi:[1,1,1]
	v_pk_fma_f32 v[22:23], v[76:77], v[118:119], v[22:23] op_sel:[1,0,0] op_sel_hi:[1,1,1]
	v_pk_fma_f32 v[18:19], v[76:77], v[120:121], v[18:19] op_sel:[1,0,0] op_sel_hi:[1,1,1]
	v_pk_fma_f32 v[16:17], v[76:77], v[122:123], v[16:17] op_sel:[1,0,0] op_sel_hi:[1,1,1]
	v_pk_fma_f32 v[14:15], v[76:77], v[124:125], v[14:15] op_sel:[1,0,0] op_sel_hi:[1,1,1]
	v_pk_fma_f32 v[12:13], v[76:77], v[126:127], v[12:13] op_sel:[1,0,0] op_sel_hi:[1,1,1]
	v_pk_fma_f32 v[10:11], v[76:77], v[128:129], v[10:11] op_sel:[1,0,0] op_sel_hi:[1,1,1]
	v_pk_fma_f32 v[4:5], v[76:77], v[130:131], v[4:5] op_sel:[1,0,0] op_sel_hi:[1,1,1]
	ds_read_b128 v[116:119], v48 offset:960
	ds_read_b128 v[120:123], v48 offset:976
	ds_read_b128 v[124:127], v48 offset:992
	ds_read_b128 v[128:131], v48 offset:1008
	s_waitcnt lgkmcnt(4)
	s_waitcnt vmcnt(17)
	v_pk_fma_f32 v[24:25], v[78:79], v[100:101], v[24:25] op_sel_hi:[0,1,1]
	v_pk_fma_f32 v[22:23], v[78:79], v[102:103], v[22:23] op_sel_hi:[0,1,1]
	v_pk_fma_f32 v[18:19], v[78:79], v[104:105], v[18:19] op_sel_hi:[0,1,1]
	v_pk_fma_f32 v[16:17], v[78:79], v[106:107], v[16:17] op_sel_hi:[0,1,1]
	v_pk_fma_f32 v[14:15], v[78:79], v[108:109], v[14:15] op_sel_hi:[0,1,1]
	v_pk_fma_f32 v[12:13], v[78:79], v[110:111], v[12:13] op_sel_hi:[0,1,1]
	v_pk_fma_f32 v[10:11], v[78:79], v[112:113], v[10:11] op_sel_hi:[0,1,1]
	v_pk_fma_f32 v[4:5], v[78:79], v[114:115], v[4:5] op_sel_hi:[0,1,1]
	ds_read_b128 v[100:103], v48 offset:1024
	ds_read_b128 v[104:107], v48 offset:1040
	ds_read_b128 v[108:111], v48 offset:1056
	ds_read_b128 v[112:115], v48 offset:1072
	s_waitcnt lgkmcnt(4)
	s_waitcnt vmcnt(16)
	v_pk_fma_f32 v[24:25], v[78:79], v[116:117], v[24:25] op_sel:[1,0,0] op_sel_hi:[1,1,1]
	v_pk_fma_f32 v[22:23], v[78:79], v[118:119], v[22:23] op_sel:[1,0,0] op_sel_hi:[1,1,1]
	v_pk_fma_f32 v[18:19], v[78:79], v[120:121], v[18:19] op_sel:[1,0,0] op_sel_hi:[1,1,1]
	v_pk_fma_f32 v[16:17], v[78:79], v[122:123], v[16:17] op_sel:[1,0,0] op_sel_hi:[1,1,1]
	v_pk_fma_f32 v[14:15], v[78:79], v[124:125], v[14:15] op_sel:[1,0,0] op_sel_hi:[1,1,1]
	v_pk_fma_f32 v[12:13], v[78:79], v[126:127], v[12:13] op_sel:[1,0,0] op_sel_hi:[1,1,1]
	v_pk_fma_f32 v[10:11], v[78:79], v[128:129], v[10:11] op_sel:[1,0,0] op_sel_hi:[1,1,1]
	v_pk_fma_f32 v[4:5], v[78:79], v[130:131], v[4:5] op_sel:[1,0,0] op_sel_hi:[1,1,1]
	ds_read_b128 v[116:119], v48 offset:1088
	ds_read_b128 v[120:123], v48 offset:1104
	ds_read_b128 v[124:127], v48 offset:1120
	ds_read_b128 v[128:131], v48 offset:1136
	s_waitcnt lgkmcnt(4)
	s_waitcnt vmcnt(15)
	v_pk_fma_f32 v[24:25], v[80:81], v[100:101], v[24:25] op_sel_hi:[0,1,1]
	v_pk_fma_f32 v[22:23], v[80:81], v[102:103], v[22:23] op_sel_hi:[0,1,1]
	v_pk_fma_f32 v[18:19], v[80:81], v[104:105], v[18:19] op_sel_hi:[0,1,1]
	v_pk_fma_f32 v[16:17], v[80:81], v[106:107], v[16:17] op_sel_hi:[0,1,1]
	v_pk_fma_f32 v[14:15], v[80:81], v[108:109], v[14:15] op_sel_hi:[0,1,1]
	v_pk_fma_f32 v[12:13], v[80:81], v[110:111], v[12:13] op_sel_hi:[0,1,1]
	v_pk_fma_f32 v[10:11], v[80:81], v[112:113], v[10:11] op_sel_hi:[0,1,1]
	v_pk_fma_f32 v[4:5], v[80:81], v[114:115], v[4:5] op_sel_hi:[0,1,1]
	ds_read_b128 v[100:103], v48 offset:1152
	ds_read_b128 v[104:107], v48 offset:1168
	ds_read_b128 v[108:111], v48 offset:1184
	ds_read_b128 v[112:115], v48 offset:1200
	s_waitcnt lgkmcnt(4)
	s_waitcnt vmcnt(14)
	v_pk_fma_f32 v[24:25], v[80:81], v[116:117], v[24:25] op_sel:[1,0,0] op_sel_hi:[1,1,1]
	v_pk_fma_f32 v[22:23], v[80:81], v[118:119], v[22:23] op_sel:[1,0,0] op_sel_hi:[1,1,1]
	v_pk_fma_f32 v[18:19], v[80:81], v[120:121], v[18:19] op_sel:[1,0,0] op_sel_hi:[1,1,1]
	v_pk_fma_f32 v[16:17], v[80:81], v[122:123], v[16:17] op_sel:[1,0,0] op_sel_hi:[1,1,1]
	v_pk_fma_f32 v[14:15], v[80:81], v[124:125], v[14:15] op_sel:[1,0,0] op_sel_hi:[1,1,1]
	v_pk_fma_f32 v[12:13], v[80:81], v[126:127], v[12:13] op_sel:[1,0,0] op_sel_hi:[1,1,1]
	v_pk_fma_f32 v[10:11], v[80:81], v[128:129], v[10:11] op_sel:[1,0,0] op_sel_hi:[1,1,1]
	v_pk_fma_f32 v[4:5], v[80:81], v[130:131], v[4:5] op_sel:[1,0,0] op_sel_hi:[1,1,1]
	ds_read_b128 v[116:119], v48 offset:1216
	ds_read_b128 v[120:123], v48 offset:1232
	ds_read_b128 v[124:127], v48 offset:1248
	ds_read_b128 v[128:131], v48 offset:1264
	s_waitcnt lgkmcnt(4)
; __device__ __forceinline__ void mod_item(const int tid, float* cs, const Params& p, int item) {
;     ...
; #pragma unroll 8
;     for (int k = 0; k < 256; ++k) {
;         const float wv = w[(size_t)k * 6144];
;         const f32x4 c0 = *(const f32x4*)(cs + k * 16), c1 = *(const f32x4*)(cs + k * 16 + 4), c2 = *(const f32x4*)(cs + k * 16 + 8), c3 = *(const f32x4*)(cs + k * 16 + 12);
; #pragma unroll
;         for (int j = 0; j < 4; ++j) { acc[j] += wv * c0[j]; acc[4 + j] += wv * c1[j]; acc[8 + j] += wv * c2[j]; acc[12 + j] += wv * c3[j]; }
;     }
	s_waitcnt vmcnt(13)
	v_pk_fma_f32 v[24:25], v[82:83], v[100:101], v[24:25] op_sel_hi:[0,1,1]
	v_pk_fma_f32 v[22:23], v[82:83], v[102:103], v[22:23] op_sel_hi:[0,1,1]
	v_pk_fma_f32 v[18:19], v[82:83], v[104:105], v[18:19] op_sel_hi:[0,1,1]
	v_pk_fma_f32 v[16:17], v[82:83], v[106:107], v[16:17] op_sel_hi:[0,1,1]
	v_pk_fma_f32 v[14:15], v[82:83], v[108:109], v[14:15] op_sel_hi:[0,1,1]
	v_pk_fma_f32 v[12:13], v[82:83], v[110:111], v[12:13] op_sel_hi:[0,1,1]
	v_pk_fma_f32 v[10:11], v[82:83], v[112:113], v[10:11] op_sel_hi:[0,1,1]
	v_pk_fma_f32 v[4:5], v[82:83], v[114:115], v[4:5] op_sel_hi:[0,1,1]
	ds_read_b128 v[100:103], v48 offset:1280
	ds_read_b128 v[104:107], v48 offset:1296
	ds_read_b128 v[108:111], v48 offset:1312
	ds_read_b128 v[112:115], v48 offset:1328
	s_waitcnt lgkmcnt(4)
	s_waitcnt vmcnt(12)
	v_pk_fma_f32 v[24:25], v[82:83], v[116:117], v[24:25] op_sel:[1,0,0] op_sel_hi:[1,1,1]
	v_pk_fma_f32 v[22:23], v[82:83], v[118:119], v[22:23] op_sel:[1,0,0] op_sel_hi:[1,1,1]
	v_pk_fma_f32 v[18:19], v[82:83], v[120:121], v[18:19] op_sel:[1,0,0] op_sel_hi:[1,1,1]
	v_pk_fma_f32 v[16:17], v[82:83], v[122:123], v[16:17] op_sel:[1,0,0] op_sel_hi:[1,1,1]
	v_pk_fma_f32 v[14:15], v[82:83], v[124:125], v[14:15] op_sel:[1,0,0] op_sel_hi:[1,1,1]
	v_pk_fma_f32 v[12:13], v[82:83], v[126:127], v[12:13] op_sel:[1,0,0] op_sel_hi:[1,1,1]
	v_pk_fma_f32 v[10:11], v[82:83], v[128:129], v[10:11] op_sel:[1,0,0] op_sel_hi:[1,1,1]
	v_pk_fma_f32 v[4:5], v[82:83], v[130:131], v[4:5] op_sel:[1,0,0] op_sel_hi:[1,1,1]
	ds_read_b128 v[116:119], v48 offset:1344
	ds_read_b128 v[120:123], v48 offset:1360
	ds_read_b128 v[124:127], v48 offset:1376
	ds_read_b128 v[128:131], v48 offset:1392
	s_waitcnt lgkmcnt(4)
	s_waitcnt vmcnt(11)
	v_pk_fma_f32 v[24:25], v[84:85], v[100:101], v[24:25] op_sel_hi:[0,1,1]
	v_pk_fma_f32 v[22:23], v[84:85], v[102:103], v[22:23] op_sel_hi:[0,1,1]
	v_pk_fma_f32 v[18:19], v[84:85], v[104:105], v[18:19] op_sel_hi:[0,1,1]
	v_pk_fma_f32 v[16:17], v[84:85], v[106:107], v[16:17] op_sel_hi:[0,1,1]
	v_pk_fma_f32 v[14:15], v[84:85], v[108:109], v[14:15] op_sel_hi:[0,1,1]
	v_pk_fma_f32 v[12:13], v[84:85], v[110:111], v[12:13] op_sel_hi:[0,1,1]
	v_pk_fma_f32 v[10:11], v[84:85], v[112:113], v[10:11] op_sel_hi:[0,1,1]
	v_pk_fma_f32 v[4:5], v[84:85], v[114:115], v[4:5] op_sel_hi:[0,1,1]
	ds_read_b128 v[100:103], v48 offset:1408
	ds_read_b128 v[104:107], v48 offset:1424
	ds_read_b128 v[108:111], v48 offset:1440
	ds_read_b128 v[112:115], v48 offset:1456
	s_waitcnt lgkmcnt(4)
	s_waitcnt vmcnt(10)
	v_pk_fma_f32 v[24:25], v[84:85], v[116:117], v[24:25] op_sel:[1,0,0] op_sel_hi:[1,1,1]
	v_pk_fma_f32 v[22:23], v[84:85], v[118:119], v[22:23] op_sel:[1,0,0] op_sel_hi:[1,1,1]
	v_pk_fma_f32 v[18:19], v[84:85], v[120:121], v[18:19] op_sel:[1,0,0] op_sel_hi:[1,1,1]
	v_pk_fma_f32 v[16:17], v[84:85], v[122:123], v[16:17] op_sel:[1,0,0] op_sel_hi:[1,1,1]
	v_pk_fma_f32 v[14:15], v[84:85], v[124:125], v[14:15] op_sel:[1,0,0] op_sel_hi:[1,1,1]
	v_pk_fma_f32 v[12:13], v[84:85], v[126:127], v[12:13] op_sel:[1,0,0] op_sel_hi:[1,1,1]
	v_pk_fma_f32 v[10:11], v[84:85], v[128:129], v[10:11] op_sel:[1,0,0] op_sel_hi:[1,1,1]
	v_pk_fma_f32 v[4:5], v[84:85], v[130:131], v[4:5] op_sel:[1,0,0] op_sel_hi:[1,1,1]
	ds_read_b128 v[116:119], v48 offset:1472
	ds_read_b128 v[120:123], v48 offset:1488
	ds_read_b128 v[124:127], v48 offset:1504
	ds_read_b128 v[128:131], v48 offset:1520
	s_waitcnt lgkmcnt(4)
	s_waitcnt vmcnt(9)
	v_pk_fma_f32 v[24:25], v[86:87], v[100:101], v[24:25] op_sel_hi:[0,1,1]
	v_pk_fma_f32 v[22:23], v[86:87], v[102:103], v[22:23] op_sel_hi:[0,1,1]
	v_pk_fma_f32 v[18:19], v[86:87], v[104:105], v[18:19] op_sel_hi:[0,1,1]
	v_pk_fma_f32 v[16:17], v[86:87], v[106:107], v[16:17] op_sel_hi:[0,1,1]
	v_pk_fma_f32 v[14:15], v[86:87], v[108:109], v[14:15] op_sel_hi:[0,1,1]
	v_pk_fma_f32 v[12:13], v[86:87], v[110:111], v[12:13] op_sel_hi:[0,1,1]
	v_pk_fma_f32 v[10:11], v[86:87], v[112:113], v[10:11] op_sel_hi:[0,1,1]
	v_pk_fma_f32 v[4:5], v[86:87], v[114:115], v[4:5] op_sel_hi:[0,1,1]
	ds_read_b128 v[100:103], v48 offset:1536
	ds_read_b128 v[104:107], v48 offset:1552
	ds_read_b128 v[108:111], v48 offset:1568
	ds_read_b128 v[112:115], v48 offset:1584
	s_waitcnt lgkmcnt(4)
	s_waitcnt vmcnt(8)
	v_pk_fma_f32 v[24:25], v[86:87], v[116:117], v[24:25] op_sel:[1,0,0] op_sel_hi:[1,1,1]
	v_pk_fma_f32 v[22:23], v[86:87], v[118:119], v[22:23] op_sel:[1,0,0] op_sel_hi:[1,1,1]
	v_pk_fma_f32 v[18:19], v[86:87], v[120:121], v[18:19] op_sel:[1,0,0] op_sel_hi:[1,1,1]
	v_pk_fma_f32 v[16:17], v[86:87], v[122:123], v[16:17] op_sel:[1,0,0] op_sel_hi:[1,1,1]
	v_pk_fma_f32 v[14:15], v[86:87], v[124:125], v[14:15] op_sel:[1,0,0] op_sel_hi:[1,1,1]
	v_pk_fma_f32 v[12:13], v[86:87], v[126:127], v[12:13] op_sel:[1,0,0] op_sel_hi:[1,1,1]
	v_pk_fma_f32 v[10:11], v[86:87], v[128:129], v[10:11] op_sel:[1,0,0] op_sel_hi:[1,1,1]
	v_pk_fma_f32 v[4:5], v[86:87], v[130:131], v[4:5] op_sel:[1,0,0] op_sel_hi:[1,1,1]
	ds_read_b128 v[116:119], v48 offset:1600
	ds_read_b128 v[120:123], v48 offset:1616
	ds_read_b128 v[124:127], v48 offset:1632
	ds_read_b128 v[128:131], v48 offset:1648
	s_waitcnt lgkmcnt(4)
	s_waitcnt vmcnt(7)
	v_pk_fma_f32 v[24:25], v[88:89], v[100:101], v[24:25] op_sel_hi:[0,1,1]
	v_pk_fma_f32 v[22:23], v[88:89], v[102:103], v[22:23] op_sel_hi:[0,1,1]
	v_pk_fma_f32 v[18:19], v[88:89], v[104:105], v[18:19] op_sel_hi:[0,1,1]
	v_pk_fma_f32 v[16:17], v[88:89], v[106:107], v[16:17] op_sel_hi:[0,1,1]
	v_pk_fma_f32 v[14:15], v[88:89], v[108:109], v[14:15] op_sel_hi:[0,1,1]
	v_pk_fma_f32 v[12:13], v[88:89], v[110:111], v[12:13] op_sel_hi:[0,1,1]
	v_pk_fma_f32 v[10:11], v[88:89], v[112:113], v[10:11] op_sel_hi:[0,1,1]
	v_pk_fma_f32 v[4:5], v[88:89], v[114:115], v[4:5] op_sel_hi:[0,1,1]
	ds_read_b128 v[100:103], v48 offset:1664
	ds_read_b128 v[104:107], v48 offset:1680
	ds_read_b128 v[108:111], v48 offset:1696
	ds_read_b128 v[112:115], v48 offset:1712
	s_waitcnt lgkmcnt(4)
; __device__ __forceinline__ void mod_item(const int tid, float* cs, const Params& p, int item) {
;     ...
; #pragma unroll 8
;     for (int k = 0; k < 256; ++k) {
;         const float wv = w[(size_t)k * 6144];
;         const f32x4 c0 = *(const f32x4*)(cs + k * 16), c1 = *(const f32x4*)(cs + k * 16 + 4), c2 = *(const f32x4*)(cs + k * 16 + 8), c3 = *(const f32x4*)(cs + k * 16 + 12);
; #pragma unroll
;         for (int j = 0; j < 4; ++j) { acc[j] += wv * c0[j]; acc[4 + j] += wv * c1[j]; acc[8 + j] += wv * c2[j]; acc[12 + j] += wv * c3[j]; }
;     }
	s_waitcnt vmcnt(6)
	v_pk_fma_f32 v[24:25], v[88:89], v[116:117], v[24:25] op_sel:[1,0,0] op_sel_hi:[1,1,1]
	v_pk_fma_f32 v[22:23], v[88:89], v[118:119], v[22:23] op_sel:[1,0,0] op_sel_hi:[1,1,1]
	v_pk_fma_f32 v[18:19], v[88:89], v[120:121], v[18:19] op_sel:[1,0,0] op_sel_hi:[1,1,1]
	v_pk_fma_f32 v[16:17], v[88:89], v[122:123], v[16:17] op_sel:[1,0,0] op_sel_hi:[1,1,1]
	v_pk_fma_f32 v[14:15], v[88:89], v[124:125], v[14:15] op_sel:[1,0,0] op_sel_hi:[1,1,1]
	v_pk_fma_f32 v[12:13], v[88:89], v[126:127], v[12:13] op_sel:[1,0,0] op_sel_hi:[1,1,1]
	v_pk_fma_f32 v[10:11], v[88:89], v[128:129], v[10:11] op_sel:[1,0,0] op_sel_hi:[1,1,1]
	v_pk_fma_f32 v[4:5], v[88:89], v[130:131], v[4:5] op_sel:[1,0,0] op_sel_hi:[1,1,1]
	ds_read_b128 v[116:119], v48 offset:1728
	ds_read_b128 v[120:123], v48 offset:1744
	ds_read_b128 v[124:127], v48 offset:1760
	ds_read_b128 v[128:131], v48 offset:1776
	s_waitcnt lgkmcnt(4)
	s_waitcnt vmcnt(5)
	v_pk_fma_f32 v[24:25], v[90:91], v[100:101], v[24:25] op_sel_hi:[0,1,1]
	v_pk_fma_f32 v[22:23], v[90:91], v[102:103], v[22:23] op_sel_hi:[0,1,1]
	v_pk_fma_f32 v[18:19], v[90:91], v[104:105], v[18:19] op_sel_hi:[0,1,1]
	v_pk_fma_f32 v[16:17], v[90:91], v[106:107], v[16:17] op_sel_hi:[0,1,1]
	v_pk_fma_f32 v[14:15], v[90:91], v[108:109], v[14:15] op_sel_hi:[0,1,1]
	v_pk_fma_f32 v[12:13], v[90:91], v[110:111], v[12:13] op_sel_hi:[0,1,1]
	v_pk_fma_f32 v[10:11], v[90:91], v[112:113], v[10:11] op_sel_hi:[0,1,1]
	v_pk_fma_f32 v[4:5], v[90:91], v[114:115], v[4:5] op_sel_hi:[0,1,1]
	ds_read_b128 v[100:103], v48 offset:1792
	ds_read_b128 v[104:107], v48 offset:1808
	ds_read_b128 v[108:111], v48 offset:1824
	ds_read_b128 v[112:115], v48 offset:1840
	s_waitcnt lgkmcnt(4)
	s_waitcnt vmcnt(4)
	v_pk_fma_f32 v[24:25], v[90:91], v[116:117], v[24:25] op_sel:[1,0,0] op_sel_hi:[1,1,1]
	v_pk_fma_f32 v[22:23], v[90:91], v[118:119], v[22:23] op_sel:[1,0,0] op_sel_hi:[1,1,1]
	v_pk_fma_f32 v[18:19], v[90:91], v[120:121], v[18:19] op_sel:[1,0,0] op_sel_hi:[1,1,1]
	v_pk_fma_f32 v[16:17], v[90:91], v[122:123], v[16:17] op_sel:[1,0,0] op_sel_hi:[1,1,1]
	v_pk_fma_f32 v[14:15], v[90:91], v[124:125], v[14:15] op_sel:[1,0,0] op_sel_hi:[1,1,1]
	v_pk_fma_f32 v[12:13], v[90:91], v[126:127], v[12:13] op_sel:[1,0,0] op_sel_hi:[1,1,1]
	v_pk_fma_f32 v[10:11], v[90:91], v[128:129], v[10:11] op_sel:[1,0,0] op_sel_hi:[1,1,1]
	v_pk_fma_f32 v[4:5], v[90:91], v[130:131], v[4:5] op_sel:[1,0,0] op_sel_hi:[1,1,1]
	ds_read_b128 v[116:119], v48 offset:1856
	ds_read_b128 v[120:123], v48 offset:1872
	ds_read_b128 v[124:127], v48 offset:1888
	ds_read_b128 v[128:131], v48 offset:1904
	s_waitcnt lgkmcnt(4)
	s_waitcnt vmcnt(3)
	v_pk_fma_f32 v[24:25], v[92:93], v[100:101], v[24:25] op_sel_hi:[0,1,1]
	v_pk_fma_f32 v[22:23], v[92:93], v[102:103], v[22:23] op_sel_hi:[0,1,1]
	v_pk_fma_f32 v[18:19], v[92:93], v[104:105], v[18:19] op_sel_hi:[0,1,1]
	v_pk_fma_f32 v[16:17], v[92:93], v[106:107], v[16:17] op_sel_hi:[0,1,1]
	v_pk_fma_f32 v[14:15], v[92:93], v[108:109], v[14:15] op_sel_hi:[0,1,1]
	v_pk_fma_f32 v[12:13], v[92:93], v[110:111], v[12:13] op_sel_hi:[0,1,1]
	v_pk_fma_f32 v[10:11], v[92:93], v[112:113], v[10:11] op_sel_hi:[0,1,1]
	v_pk_fma_f32 v[4:5], v[92:93], v[114:115], v[4:5] op_sel_hi:[0,1,1]
	ds_read_b128 v[100:103], v48 offset:1920
	ds_read_b128 v[104:107], v48 offset:1936
	ds_read_b128 v[108:111], v48 offset:1952
	ds_read_b128 v[112:115], v48 offset:1968
	s_waitcnt lgkmcnt(4)
	s_waitcnt vmcnt(2)
	v_pk_fma_f32 v[24:25], v[92:93], v[116:117], v[24:25] op_sel:[1,0,0] op_sel_hi:[1,1,1]
	v_pk_fma_f32 v[22:23], v[92:93], v[118:119], v[22:23] op_sel:[1,0,0] op_sel_hi:[1,1,1]
	v_pk_fma_f32 v[18:19], v[92:93], v[120:121], v[18:19] op_sel:[1,0,0] op_sel_hi:[1,1,1]
	v_pk_fma_f32 v[16:17], v[92:93], v[122:123], v[16:17] op_sel:[1,0,0] op_sel_hi:[1,1,1]
	v_pk_fma_f32 v[14:15], v[92:93], v[124:125], v[14:15] op_sel:[1,0,0] op_sel_hi:[1,1,1]
	v_pk_fma_f32 v[12:13], v[92:93], v[126:127], v[12:13] op_sel:[1,0,0] op_sel_hi:[1,1,1]
	v_pk_fma_f32 v[10:11], v[92:93], v[128:129], v[10:11] op_sel:[1,0,0] op_sel_hi:[1,1,1]
	v_pk_fma_f32 v[4:5], v[92:93], v[130:131], v[4:5] op_sel:[1,0,0] op_sel_hi:[1,1,1]
	ds_read_b128 v[116:119], v48 offset:1984
	ds_read_b128 v[120:123], v48 offset:2000
	ds_read_b128 v[124:127], v48 offset:2016
	ds_read_b128 v[128:131], v48 offset:2032
	s_waitcnt lgkmcnt(4)
; __device__ __forceinline__ void mod_item(const int tid, float* cs, const Params& p, int item) {
;     ...
; #pragma unroll 8
;     for (int k = 0; k < 256; ++k) {
;         const float wv = w[(size_t)k * 6144];
;         const f32x4 c0 = *(const f32x4*)(cs + k * 16), c1 = *(const f32x4*)(cs + k * 16 + 4), c2 = *(const f32x4*)(cs + k * 16 + 8), c3 = *(const f32x4*)(cs + k * 16 + 12);
; #pragma unroll
;         for (int j = 0; j < 4; ++j) { acc[j] += wv * c0[j]; acc[4 + j] += wv * c1[j]; acc[8 + j] += wv * c2[j]; acc[12 + j] += wv * c3[j]; }
;     }
;     float* part = (float*)(p.ws + WS_MODP) + ((size_t)s * 2 + l) * 16 * 6144 + col;
; #pragma unroll
;     for (int r = 0; r < 16; ++r) part[(size_t)r * 6144] = acc[r];
	s_waitcnt vmcnt(1)
	v_pk_fma_f32 v[24:25], v[94:95], v[100:101], v[24:25] op_sel_hi:[0,1,1]
	v_pk_fma_f32 v[22:23], v[94:95], v[102:103], v[22:23] op_sel_hi:[0,1,1]
	v_pk_fma_f32 v[18:19], v[94:95], v[104:105], v[18:19] op_sel_hi:[0,1,1]
	v_pk_fma_f32 v[16:17], v[94:95], v[106:107], v[16:17] op_sel_hi:[0,1,1]
	v_pk_fma_f32 v[14:15], v[94:95], v[108:109], v[14:15] op_sel_hi:[0,1,1]
	v_pk_fma_f32 v[12:13], v[94:95], v[110:111], v[12:13] op_sel_hi:[0,1,1]
	v_pk_fma_f32 v[10:11], v[94:95], v[112:113], v[10:11] op_sel_hi:[0,1,1]
	v_pk_fma_f32 v[4:5], v[94:95], v[114:115], v[4:5] op_sel_hi:[0,1,1]
	s_waitcnt lgkmcnt(0)
	s_waitcnt vmcnt(0)
	v_pk_fma_f32 v[24:25], v[94:95], v[116:117], v[24:25] op_sel:[1,0,0] op_sel_hi:[1,1,1]
	v_pk_fma_f32 v[22:23], v[94:95], v[118:119], v[22:23] op_sel:[1,0,0] op_sel_hi:[1,1,1]
	v_pk_fma_f32 v[18:19], v[94:95], v[120:121], v[18:19] op_sel:[1,0,0] op_sel_hi:[1,1,1]
	v_pk_fma_f32 v[16:17], v[94:95], v[122:123], v[16:17] op_sel:[1,0,0] op_sel_hi:[1,1,1]
	v_pk_fma_f32 v[14:15], v[94:95], v[124:125], v[14:15] op_sel:[1,0,0] op_sel_hi:[1,1,1]
	v_pk_fma_f32 v[12:13], v[94:95], v[126:127], v[12:13] op_sel:[1,0,0] op_sel_hi:[1,1,1]
	v_pk_fma_f32 v[10:11], v[94:95], v[128:129], v[10:11] op_sel:[1,0,0] op_sel_hi:[1,1,1]
	v_pk_fma_f32 v[4:5], v[94:95], v[130:131], v[4:5] op_sel:[1,0,0] op_sel_hi:[1,1,1]
	s_mul_hi_i32 s4, s15, 0xc0000
	s_mul_i32 s15, s15, 0xc0000
	s_add_u32 s15, s18, s15
	s_mul_hi_i32 s5, s14, 0x60000
	s_mul_i32 s14, s14, 0x60000
	s_addc_u32 s21, s19, s4
	s_add_u32 s4, s15, s14
	s_addc_u32 s5, s21, s5
	v_lshl_add_u64 v[6:7], v[6:7], 2, s[4:5]
	v_add_co_u32_e32 v8, vcc, s94, v6
	s_mov_b32 s4, 0x36000
	s_nop 0
	v_addc_co_u32_e32 v9, vcc, 0, v7, vcc
	global_store_dword v[8:9], v25, off
	v_add_co_u32_e32 v8, vcc, s34, v6
	global_store_dword v[6:7], v24, off
	s_nop 0
	v_addc_co_u32_e32 v9, vcc, 0, v7, vcc
	global_store_dword v[8:9], v22, off
	v_add_co_u32_e32 v8, vcc, s92, v6
	s_nop 1
	v_addc_co_u32_e32 v9, vcc, 0, v7, vcc
	global_store_dword v[8:9], v23, off
	v_add_co_u32_e32 v8, vcc, s96, v6
	s_nop 1
	v_addc_co_u32_e32 v9, vcc, 0, v7, vcc
	global_store_dword v[8:9], v18, off
	v_add_co_u32_e32 v8, vcc, s33, v6
	s_nop 1
	v_addc_co_u32_e32 v9, vcc, 0, v7, vcc
	global_store_dword v[8:9], v19, off
	v_add_co_u32_e32 v8, vcc, s95, v6
	s_nop 1
	v_addc_co_u32_e32 v9, vcc, 0, v7, vcc
	global_store_dword v[8:9], v16, off
	v_add_co_u32_e32 v8, vcc, s38, v6
	s_nop 1
	v_addc_co_u32_e32 v9, vcc, 0, v7, vcc
	global_store_dword v[8:9], v17, off
	v_add_co_u32_e32 v8, vcc, s0, v6
	s_nop 1
	v_addc_co_u32_e32 v9, vcc, 0, v7, vcc
	global_store_dword v[8:9], v14, off
	v_add_co_u32_e32 v8, vcc, s4, v6
	s_mov_b32 s4, 0x3c000
	s_nop 0
	v_addc_co_u32_e32 v9, vcc, 0, v7, vcc
	global_store_dword v[8:9], v15, off
	v_add_co_u32_e32 v8, vcc, s4, v6
	s_mov_b32 s4, 0x42000
	s_nop 0
	v_addc_co_u32_e32 v9, vcc, 0, v7, vcc
	global_store_dword v[8:9], v12, off
	v_add_co_u32_e32 v8, vcc, s4, v6
	s_mov_b32 s4, 0x48000
	s_nop 0
	v_addc_co_u32_e32 v9, vcc, 0, v7, vcc
	global_store_dword v[8:9], v13, off
	v_add_co_u32_e32 v8, vcc, s4, v6
	s_nop 1
	v_addc_co_u32_e32 v9, vcc, 0, v7, vcc
	global_store_dword v[8:9], v10, off
	v_add_co_u32_e32 v8, vcc, 0x4e000, v6
	s_nop 1
	v_addc_co_u32_e32 v9, vcc, 0, v7, vcc
	global_store_dword v[8:9], v11, off
	v_add_co_u32_e32 v8, vcc, 0x54000, v6
	s_nop 1
	v_addc_co_u32_e32 v9, vcc, 0, v7, vcc
	v_add_co_u32_e32 v6, vcc, 0x5a000, v6
	global_store_dword v[8:9], v4, off
	s_nop 0
	v_addc_co_u32_e32 v7, vcc, 0, v7, vcc
	global_store_dword v[6:7], v5, off
	s_barrier
	s_branch .LBB0_802
